# S5 pass 2: second work item of each workgroup takes the mirrored chunk group (jg -> 3-jg) so long and short carry chains are balanced across workgroups
# speedup vs baseline: 1.0069x; 1.0069x over previous
; __device__ __forceinline__ PP get_pp() { PP q = (PP)__builtin_amdgcn_kernarg_segment_ptr(); asm volatile("" : "+s"(q)); return q; }
; __device__ __forceinline__ int bid_fresh() { int t = blockIdx.x; asm volatile("" : "+s"(t)); return t; }
; __device__ __forceinline__ void s5_pass2_item(PP p, unsigned char* shm, int item, int l) {
;     ...
;     __syncthreads();
;     S5Frag f; s5_load_frags(bbL, f, lane);
;     const float dsk = p->in[13][(size_t)l * 512 + g * 16 + cc];
;     bf16_t* Gout = (bf16_t*)(p->ws + WS_GPH);
;     for (int sc = 0; sc < 4; ++sc) {
;         s5_bu16(f, uf[sc], buL, lane);
;         __syncthreads();
; #pragma unroll
;         for (int t = 0; t < 16; ++t) { s5_rec(q, *(const f32x2*)(buL + (t * 64 + lane) * 2), x); xs[t * 132 + lane] = x.x; xs[t * 132 + 64 + lane] = x.y; }
; __global__ void __launch_bounds__(512, 2) hymba_fwd(Params p_unused) {
;     ...
;         for (int rep = 0; rep < P3_REPS; ++rep) for (int it = bid_fresh(); it < 512; it += gridDim.x) s5_pass2_item(get_pp(), shm, it, l);
.LBB0_679:
	s_or_b64 exec, exec, s[2:3]
	s_movk_i32 s2, 0x2100
	v_mul_lo_u32 v0, v93, s2
	s_add_i32 s2, 0, 0x11000
	v_add_u32_e32 v102, s2, v0
	s_load_dwordx2 s[2:3], s[12:13], 0x68
	v_lshl_add_u32 v0, v93, 13, 0
	v_mul_f32_e32 v77, v77, v97
	v_mul_f32_e32 v76, v76, v97
	v_mul_f32_e32 v75, v75, v97
	s_waitcnt lgkmcnt(0)
	s_add_u32 s12, s2, s18
	s_addc_u32 s13, s3, 0
	s_lshl_b64 s[2:3], s[34:35], 2
	s_add_u32 s2, s12, s2
	v_mul_f32_e32 v74, v74, v97
	v_mul_f32_e32 v73, v73, v97
	v_mul_f32_e32 v72, v72, v97
	v_mul_f32_e32 v71, v71, v97
	v_mul_f32_e32 v70, v70, v97
	v_mul_f32_e32 v69, v69, v97
	v_mul_f32_e32 v68, v68, v97
	v_mul_f32_e32 v67, v67, v97
	v_mul_f32_e32 v66, v66, v97
	v_mul_f32_e32 v65, v65, v97
	v_mul_f32_e32 v64, v64, v97
	v_mul_f32_e32 v63, v63, v97
	v_mul_f32_e32 v62, v62, v97
	v_mul_f32_e32 v61, v61, v97
	v_mul_f32_e32 v60, v60, v97
	v_mul_f32_e32 v59, v59, v97
	v_mul_f32_e32 v58, v58, v97
	v_mul_f32_e32 v57, v57, v97
	v_mul_f32_e32 v56, v56, v97
	v_mul_f32_e32 v55, v55, v97
	v_mul_f32_e32 v85, v54, v97
	v_mul_f32_e32 v88, v53, v97
	v_mul_f32_e32 v91, v52, v97
	v_mul_f32_e32 v92, v51, v97
	v_mul_f32_e32 v93, v50, v97
	v_mul_f32_e32 v94, v49, v97
	v_mul_f32_e32 v95, v48, v97
	v_mul_f32_e32 v96, v47, v97
	v_mul_f32_e32 v97, v46, v97
	s_addc_u32 s3, s13, s3
	v_lshlrev_b32_e32 v46, 2, v100
	global_load_dword v54, v46, s[2:3]
	v_and_b32_e32 v46, 0x600, v99
	v_lshl_add_u32 v46, v46, 2, v0
	v_and_b32_e32 v47, 0x78, v90
	v_add_u32_e32 v108, v46, v47
	v_or_b32_e32 v47, 0x180, v90
	v_add_u32_e32 v99, v46, v47
	v_mul_u32_u24_e32 v46, 0x210, v100
	v_lshlrev_b32_e32 v47, 2, v101
	v_add_u32_e32 v90, v0, v90
	v_mov_b32_e32 v0, v89
	v_lshl_add_u32 v98, v98, 2, v102
	v_add3_u32 v89, v102, v46, v47
	v_or_b32_e32 v50, s34, v100
	v_mfma_f32_16x16x32_bf16 v[46:49], v[78:81], v[26:29], 0
	v_add_u32_e32 v108, 0x1000, v108
	v_lshl_or_b32 v82, v109, 2, v82
	v_mov_b32_e32 v51, s35
	v_mfma_f32_16x16x32_bf16 v[100:103], v[78:81], v[34:37], 0
	s_add_u32 s28, s28, 0x21600000
	s_nop 2
	v_mov_b32_e32 v52, v46
	v_mov_b32_e32 v110, v48
	v_mfma_f32_16x16x32_bf16 v[104:107], v[78:81], v[30:33], 0
	s_addc_u32 s29, s29, 0
	v_mov_b32_e32 v53, v100
	v_mov_b32_e32 v100, v47
	v_mov_b32_e32 v111, v102
	v_mov_b32_e32 v102, v49
	v_mfma_f32_16x16x32_bf16 v[46:49], v[78:81], v[22:25], 0
	s_nop 1
	v_mov_b32_e32 v113, v104
	s_xor_b32 s14, s14, 3
	s_add_i32 s14, s14, s66
	s_cmpk_gt_i32 s14, 0x1ff
	s_nop 2
	v_mov_b32_e32 v112, v46
	v_mov_b32_e32 v104, v47
	v_mov_b32_e32 v46, v48
	v_mov_b32_e32 v47, v106
	ds_write2_b64 v108, v[52:53], v[112:113] offset1:16
	ds_write2_b64 v108, v[110:111], v[46:47] offset0:128 offset1:144
	v_mov_b32_e32 v106, v49
	v_mfma_f32_16x16x32_bf16 v[46:49], v[78:81], v[18:21], 0
	v_mfma_f32_16x16x32_bf16 v[110:113], v[78:81], v[14:17], 0
	s_nop 6
	v_mov_b32_e32 v52, v46
	v_mov_b32_e32 v53, v110
	v_mov_b32_e32 v110, v47
	v_mov_b32_e32 v46, v48
	v_mov_b32_e32 v47, v112
	ds_write2_b64 v108, v[46:47], v[102:103] offset0:160 offset1:192
	v_mov_b32_e32 v112, v49
	v_mfma_f32_16x16x32_bf16 v[46:49], v[78:81], v[10:13], 0
	ds_write2_b64 v108, v[52:53], v[100:101] offset0:32 offset1:64
	ds_write2_b64 v108, v[104:105], v[110:111] offset0:80 offset1:96
	ds_write2_b64 v108, v[106:107], v[112:113] offset0:208 offset1:224
	v_mfma_f32_16x16x32_bf16 v[78:81], v[78:81], v[6:9], 0
	v_add_u32_e32 v100, 0x80, v98
	s_nop 2
	v_mov_b32_e32 v52, v46
	v_mov_b32_e32 v46, v48
	v_xor_b32_e32 v48, 0x80000000, v87
	v_add_u32_e32 v101, 0x90, v98
	v_mov_b32_e32 v53, v78
	v_mov_b32_e32 v78, v47
	v_mov_b32_e32 v47, v80
	v_mov_b32_e32 v80, v49
	ds_write2st64_b64 v99, v[52:53], v[78:79] offset0:8 offset1:9
	ds_write2st64_b64 v99, v[46:47], v[80:81] offset0:10 offset1:11
	s_waitcnt lgkmcnt(0)
	s_barrier
	ds_read_b64 v[46:47], v90 offset:4096
	v_mov_b32_e32 v49, v86
	v_pk_mul_f32 v[48:49], v[0:1], v[48:49] op_sel_hi:[0,1]
	v_pk_fma_f32 v[48:49], v[84:85], v[86:87], v[48:49] op_sel_hi:[0,1,1]
	v_add_u32_e32 v78, 32, v98
	s_waitcnt lgkmcnt(0)
	v_pk_add_f32 v[46:47], v[48:49], v[46:47]
	ds_write2st64_b32 v98, v46, v47 offset1:1
	ds_read_b64 v[48:49], v90 offset:4608
	v_xor_b32_e32 v52, 0x80000000, v47
	v_mov_b32_e32 v53, v46
	v_pk_mul_f32 v[52:53], v[0:1], v[52:53] op_sel_hi:[0,1]
	v_pk_fma_f32 v[46:47], v[84:85], v[46:47], v[52:53] op_sel_hi:[0,1,1]
	s_waitcnt lgkmcnt(0)
	v_pk_add_f32 v[46:47], v[48:49], v[46:47]
	ds_write2_b32 v98, v46, v47 offset0:132 offset1:196
	ds_read_b64 v[48:49], v90 offset:5120
	v_xor_b32_e32 v52, 0x80000000, v47
	v_mov_b32_e32 v53, v46
	v_pk_mul_f32 v[52:53], v[0:1], v[52:53] op_sel_hi:[0,1]
	v_pk_fma_f32 v[46:47], v[84:85], v[46:47], v[52:53] op_sel_hi:[0,1,1]
	s_waitcnt lgkmcnt(0)
	v_pk_add_f32 v[46:47], v[48:49], v[46:47]
	ds_write2st64_b32 v78, v46, v47 offset0:4 offset1:5
	ds_read_b64 v[48:49], v90 offset:5632
	v_xor_b32_e32 v52, 0x80000000, v47
	v_mov_b32_e32 v53, v46
	v_pk_mul_f32 v[52:53], v[0:1], v[52:53] op_sel_hi:[0,1]
	v_pk_fma_f32 v[46:47], v[84:85], v[46:47], v[52:53] op_sel_hi:[0,1,1]
	s_waitcnt lgkmcnt(0)
	v_pk_add_f32 v[46:47], v[48:49], v[46:47]
	v_add_u32_e32 v79, 48, v98
	ds_write2st64_b32 v79, v46, v47 offset0:6 offset1:7
	ds_read_b64 v[48:49], v90 offset:6144
	v_xor_b32_e32 v52, 0x80000000, v47
	v_mov_b32_e32 v53, v46
	v_pk_mul_f32 v[52:53], v[0:1], v[52:53] op_sel_hi:[0,1]
	v_pk_fma_f32 v[46:47], v[84:85], v[46:47], v[52:53] op_sel_hi:[0,1,1]
	s_waitcnt lgkmcnt(0)
	v_pk_add_f32 v[46:47], v[48:49], v[46:47]
	v_add_u32_e32 v80, 64, v98
	ds_write2st64_b32 v80, v46, v47 offset0:8 offset1:9
	ds_read_b64 v[48:49], v90 offset:6656
	v_xor_b32_e32 v52, 0x80000000, v47
	v_mov_b32_e32 v53, v46
	v_pk_mul_f32 v[52:53], v[0:1], v[52:53] op_sel_hi:[0,1]
	v_pk_fma_f32 v[46:47], v[84:85], v[46:47], v[52:53] op_sel_hi:[0,1,1]
	s_waitcnt lgkmcnt(0)
; __device__ __forceinline__ float bf2f(bf16_t v) { return __uint_as_float(((unsigned)v) << 16); }
; __device__ __forceinline__ void s5_pass2_item(PP p, unsigned char* shm, int item, int l) {
;     ...
;         for (int t = 0; t < 16; ++t) { s5_rec(q, *(const f32x2*)(buL + (t * 64 + lane) * 2), x); xs[t * 132 + lane] = x.x; xs[t * 132 + 64 + lane] = x.y; }
;         __syncthreads();
;         f32x4 y0 = (f32x4){0.f, 0.f, 0.f, 0.f}, y1 = y0;
;         const f32x4* xrow = (const f32x4*)(xs + cc * 132 + quad * 32);
; #pragma unroll
;         for (int i = 0; i < 8; ++i) { const f32x4 xv = xrow[i];
;             y0 = __builtin_amdgcn_mfma_f32_16x16x4f32(xv[0], cmr[4 * i + 0], y0, 0, 0, 0);
;             y1 = __builtin_amdgcn_mfma_f32_16x16x4f32(xv[1], cmr[4 * i + 1], y1, 0, 0, 0);
;             y0 = __builtin_amdgcn_mfma_f32_16x16x4f32(xv[2], cmr[4 * i + 2], y0, 0, 0, 0);
;             y1 = __builtin_amdgcn_mfma_f32_16x16x4f32(xv[3], cmr[4 * i + 3], y1, 0, 0, 0); }
;         const f32x4 y = y0 + y1;
; #pragma unroll
;         for (int r = 0; r < 4; ++r) { const int tl = sc * 16 + quad * 4 + r;
;             const float v = y[r] + dsk * bf2f(proj[PJ_UA + (row0 + tl) * 512 + g * 16 + cc]);
	v_pk_add_f32 v[46:47], v[48:49], v[46:47]
	v_add_u32_e32 v81, 0x50, v98
	ds_write2st64_b32 v81, v46, v47 offset0:10 offset1:11
	ds_read_b64 v[48:49], v90 offset:7168
	v_xor_b32_e32 v52, 0x80000000, v47
	v_mov_b32_e32 v53, v46
	v_pk_mul_f32 v[52:53], v[0:1], v[52:53] op_sel_hi:[0,1]
	v_pk_fma_f32 v[46:47], v[84:85], v[46:47], v[52:53] op_sel_hi:[0,1,1]
	s_waitcnt lgkmcnt(0)
	v_pk_add_f32 v[46:47], v[48:49], v[46:47]
	v_add_u32_e32 v86, 0x60, v98
	ds_write2st64_b32 v86, v46, v47 offset0:12 offset1:13
	ds_read_b64 v[48:49], v90 offset:7680
	v_xor_b32_e32 v52, 0x80000000, v47
	v_mov_b32_e32 v53, v46
	v_pk_mul_f32 v[52:53], v[0:1], v[52:53] op_sel_hi:[0,1]
	v_pk_fma_f32 v[46:47], v[84:85], v[46:47], v[52:53] op_sel_hi:[0,1,1]
	s_waitcnt lgkmcnt(0)
	v_pk_add_f32 v[46:47], v[48:49], v[46:47]
	v_add_u32_e32 v87, 0x70, v98
	ds_write2st64_b32 v87, v46, v47 offset0:14 offset1:15
	ds_read_b64 v[48:49], v90 offset:8192
	v_xor_b32_e32 v52, 0x80000000, v47
	v_mov_b32_e32 v53, v46
	v_pk_mul_f32 v[52:53], v[0:1], v[52:53] op_sel_hi:[0,1]
	v_pk_fma_f32 v[46:47], v[84:85], v[46:47], v[52:53] op_sel_hi:[0,1,1]
	s_waitcnt lgkmcnt(0)
	v_pk_add_f32 v[46:47], v[48:49], v[46:47]
	ds_write2st64_b32 v100, v46, v47 offset0:16 offset1:17
	ds_read_b64 v[48:49], v90 offset:8704
	v_xor_b32_e32 v52, 0x80000000, v47
	v_mov_b32_e32 v53, v46
	v_pk_mul_f32 v[52:53], v[0:1], v[52:53] op_sel_hi:[0,1]
	v_pk_fma_f32 v[46:47], v[84:85], v[46:47], v[52:53] op_sel_hi:[0,1,1]
	s_waitcnt lgkmcnt(0)
	v_pk_add_f32 v[46:47], v[48:49], v[46:47]
	ds_write2st64_b32 v101, v46, v47 offset0:18 offset1:19
	ds_read_b64 v[48:49], v90 offset:9216
	v_xor_b32_e32 v52, 0x80000000, v47
	v_mov_b32_e32 v53, v46
	v_pk_mul_f32 v[52:53], v[0:1], v[52:53] op_sel_hi:[0,1]
	v_pk_fma_f32 v[46:47], v[84:85], v[46:47], v[52:53] op_sel_hi:[0,1,1]
	s_waitcnt lgkmcnt(0)
	v_pk_add_f32 v[46:47], v[48:49], v[46:47]
	v_add_u32_e32 v102, 0xa0, v98
	ds_write2st64_b32 v102, v46, v47 offset0:20 offset1:21
	ds_read_b64 v[48:49], v90 offset:9728
	v_xor_b32_e32 v52, 0x80000000, v47
	v_mov_b32_e32 v53, v46
	v_pk_mul_f32 v[52:53], v[0:1], v[52:53] op_sel_hi:[0,1]
	v_pk_fma_f32 v[46:47], v[84:85], v[46:47], v[52:53] op_sel_hi:[0,1,1]
	s_waitcnt lgkmcnt(0)
	v_pk_add_f32 v[46:47], v[48:49], v[46:47]
	v_add_u32_e32 v103, 0xb0, v98
	ds_write2st64_b32 v103, v46, v47 offset0:22 offset1:23
	ds_read_b64 v[48:49], v90 offset:10240
	v_xor_b32_e32 v52, 0x80000000, v47
	v_mov_b32_e32 v53, v46
	v_pk_mul_f32 v[52:53], v[0:1], v[52:53] op_sel_hi:[0,1]
	v_pk_fma_f32 v[46:47], v[84:85], v[46:47], v[52:53] op_sel_hi:[0,1,1]
	s_waitcnt lgkmcnt(0)
	v_pk_add_f32 v[46:47], v[48:49], v[46:47]
	v_add_u32_e32 v104, 0xc0, v98
	ds_write2st64_b32 v104, v46, v47 offset0:24 offset1:25
	ds_read_b64 v[48:49], v90 offset:10752
	v_xor_b32_e32 v52, 0x80000000, v47
	v_mov_b32_e32 v53, v46
	v_pk_mul_f32 v[52:53], v[0:1], v[52:53] op_sel_hi:[0,1]
	v_pk_fma_f32 v[46:47], v[84:85], v[46:47], v[52:53] op_sel_hi:[0,1,1]
	s_waitcnt lgkmcnt(0)
	v_pk_add_f32 v[46:47], v[48:49], v[46:47]
	v_add_u32_e32 v105, 0xd0, v98
	ds_write2st64_b32 v105, v46, v47 offset0:26 offset1:27
	ds_read_b64 v[48:49], v90 offset:11264
	v_xor_b32_e32 v52, 0x80000000, v47
	v_mov_b32_e32 v53, v46
	v_pk_mul_f32 v[52:53], v[0:1], v[52:53] op_sel_hi:[0,1]
	v_pk_fma_f32 v[46:47], v[84:85], v[46:47], v[52:53] op_sel_hi:[0,1,1]
	s_waitcnt lgkmcnt(0)
	v_pk_add_f32 v[46:47], v[48:49], v[46:47]
	v_add_u32_e32 v106, 0xe0, v98
	ds_write2st64_b32 v106, v46, v47 offset0:28 offset1:29
	ds_read_b64 v[48:49], v90 offset:11776
	v_xor_b32_e32 v52, 0x80000000, v47
	v_mov_b32_e32 v53, v46
	v_pk_mul_f32 v[52:53], v[0:1], v[52:53] op_sel_hi:[0,1]
	v_pk_fma_f32 v[46:47], v[84:85], v[46:47], v[52:53] op_sel_hi:[0,1,1]
	s_waitcnt lgkmcnt(0)
	v_pk_add_f32 v[52:53], v[48:49], v[46:47]
	v_add_u32_e32 v107, 0xf0, v98
	ds_write2st64_b32 v107, v52, v53 offset0:30 offset1:31
	s_waitcnt lgkmcnt(0)
	s_barrier
	v_mov_b32_e32 v216, v82
	v_mov_b32_e32 v217, v83
	v_lshlrev_b64 v[216:217], 9, v[216:217]
	v_lshl_add_u64 v[216:217], v[216:217], 0, v[50:51]
	v_lshlrev_b64 v[216:217], 1, v[216:217]
	v_lshl_add_u64 v[216:217], s[8:9], 0, v[216:217]
	global_load_ushort v200, v[216:217], off
	global_load_ushort v201, v[216:217], off offset:1024
	global_load_ushort v202, v[216:217], off offset:2048
	global_load_ushort v203, v[216:217], off offset:3072
	ds_read_b128 v[46:49], v89
	ds_read_b128 v[110:113], v89 offset:16
	ds_read_b128 v[114:117], v89 offset:32
	ds_read_b128 v[118:121], v89 offset:48
	s_waitcnt lgkmcnt(3)
	v_mfma_f32_16x16x4_f32 v[122:125], v46, v97, 0
	v_mfma_f32_16x16x4_f32 v[126:129], v47, v96, 0
	v_mfma_f32_16x16x4_f32 v[122:125], v48, v95, v[122:125]
	v_mfma_f32_16x16x4_f32 v[46:49], v49, v94, v[126:129]
	s_waitcnt lgkmcnt(2)
	v_mfma_f32_16x16x4_f32 v[122:125], v110, v93, v[122:125]
	v_mfma_f32_16x16x4_f32 v[46:49], v111, v92, v[46:49]
	v_mfma_f32_16x16x4_f32 v[122:125], v112, v91, v[122:125]
	v_mfma_f32_16x16x4_f32 v[46:49], v113, v88, v[46:49]
	s_waitcnt lgkmcnt(1)
	v_mfma_f32_16x16x4_f32 v[110:113], v114, v85, v[122:125]
	v_mfma_f32_16x16x4_f32 v[46:49], v115, v55, v[46:49]
	v_mfma_f32_16x16x4_f32 v[110:113], v116, v56, v[110:113]
	v_mfma_f32_16x16x4_f32 v[46:49], v117, v57, v[46:49]
	ds_read_b128 v[114:117], v89 offset:64
	s_waitcnt lgkmcnt(1)
	v_mfma_f32_16x16x4_f32 v[110:113], v118, v58, v[110:113]
	v_mfma_f32_16x16x4_f32 v[46:49], v119, v59, v[46:49]
	v_mfma_f32_16x16x4_f32 v[110:113], v120, v60, v[110:113]
	v_mfma_f32_16x16x4_f32 v[46:49], v121, v61, v[46:49]
	s_waitcnt lgkmcnt(0)
; __device__ __forceinline__ float bf2f(bf16_t v) { return __uint_as_float(((unsigned)v) << 16); }
; __device__ __forceinline__ bf16_t f2bf(float f) { unsigned u = __float_as_uint(f); u += 0x7FFFu + ((u >> 16) & 1u); return (bf16_t)(u >> 16); }
; __device__ __forceinline__ void s5_bu16(const S5Frag& f, const bf16x8 uf, float* buL, int lane) {
;     const int jj = lane & 15, quad = lane >> 4;
; #pragma unroll
;     for (int nt = 0; nt < 4; ++nt) {
;         const f32x4 z = (f32x4){0.f, 0.f, 0.f, 0.f};
;         const f32x4 dre = __builtin_amdgcn_mfma_f32_16x16x32_bf16(uf, f.bfr[nt], z, 0, 0, 0);
;         const f32x4 dim = __builtin_amdgcn_mfma_f32_16x16x32_bf16(uf, f.bfr[nt + 4], z, 0, 0, 0);
; #pragma unroll
;         for (int r = 0; r < 4; ++r) *(f32x2*)(buL + ((4 * quad + r) * 64 + 16 * nt + jj) * 2) = (f32x2){dre[r], dim[r]};
; __device__ __forceinline__ void s5_pass2_item(PP p, unsigned char* shm, int item, int l) {
;     ...
;         f32x4 y0 = (f32x4){0.f, 0.f, 0.f, 0.f}, y1 = y0;
;         const f32x4* xrow = (const f32x4*)(xs + cc * 132 + quad * 32);
; #pragma unroll
;         for (int i = 0; i < 8; ++i) { const f32x4 xv = xrow[i];
;             y0 = __builtin_amdgcn_mfma_f32_16x16x4f32(xv[0], cmr[4 * i + 0], y0, 0, 0, 0);
;             y1 = __builtin_amdgcn_mfma_f32_16x16x4f32(xv[1], cmr[4 * i + 1], y1, 0, 0, 0);
;             y0 = __builtin_amdgcn_mfma_f32_16x16x4f32(xv[2], cmr[4 * i + 2], y0, 0, 0, 0);
;             y1 = __builtin_amdgcn_mfma_f32_16x16x4f32(xv[3], cmr[4 * i + 3], y1, 0, 0, 0); }
;         const f32x4 y = y0 + y1;
; #pragma unroll
;         for (int r = 0; r < 4; ++r) { const int tl = sc * 16 + quad * 4 + r;
;             const float v = y[r] + dsk * bf2f(proj[PJ_UA + (row0 + tl) * 512 + g * 16 + cc]);
;             const float z = 0.7978845608028654f * (v + 0.044715f * v * v * v);
;             const float th = 1.0f - 2.0f / (__expf(2.0f * z) + 1.0f);
;             Gout[(row0 + tl) * 512 + g * 16 + cc] = f2bf(0.5f * v * (1.0f + th)); }
	v_mfma_f32_16x16x4_f32 v[110:113], v114, v62, v[110:113]
	v_mfma_f32_16x16x4_f32 v[46:49], v115, v63, v[46:49]
	v_mfma_f32_16x16x4_f32 v[110:113], v116, v64, v[110:113]
	v_mfma_f32_16x16x4_f32 v[46:49], v117, v65, v[46:49]
	ds_read_b128 v[114:117], v89 offset:80
	s_waitcnt lgkmcnt(0)
	v_mfma_f32_16x16x4_f32 v[110:113], v114, v66, v[110:113]
	v_mfma_f32_16x16x4_f32 v[46:49], v115, v67, v[46:49]
	v_mfma_f32_16x16x4_f32 v[110:113], v116, v68, v[110:113]
	v_mfma_f32_16x16x4_f32 v[46:49], v117, v69, v[46:49]
	ds_read_b128 v[114:117], v89 offset:96
	s_waitcnt lgkmcnt(0)
	v_mfma_f32_16x16x4_f32 v[110:113], v114, v70, v[110:113]
	v_mfma_f32_16x16x4_f32 v[46:49], v115, v71, v[46:49]
	v_mfma_f32_16x16x4_f32 v[110:113], v116, v72, v[110:113]
	v_mfma_f32_16x16x4_f32 v[46:49], v117, v73, v[46:49]
	ds_read_b128 v[114:117], v89 offset:112
	s_waitcnt lgkmcnt(0)
	v_mfma_f32_16x16x4_f32 v[110:113], v114, v74, v[110:113]
	v_mfma_f32_16x16x4_f32 v[46:49], v115, v75, v[46:49]
	v_mfma_f32_16x16x4_f32 v[110:113], v116, v76, v[110:113]
	v_mfma_f32_16x16x4_f32 v[46:49], v117, v77, v[46:49]
	s_nop 9
	v_pk_add_f32 v[46:47], v[110:111], v[46:47]
	v_lshlrev_b64 v[110:111], 9, v[82:83]
	v_lshl_add_u64 v[110:111], v[110:111], 0, v[50:51]
	v_lshlrev_b64 v[110:111], 1, v[110:111]
	v_pk_add_f32 v[48:49], v[112:113], v[48:49]
	v_lshl_add_u64 v[112:113], s[8:9], 0, v[110:111]
	v_lshl_add_u64 v[110:111], s[28:29], 0, v[110:111]
	s_waitcnt vmcnt(3)
	v_lshlrev_b32_e32 v109, 16, v200
	v_fma_f32 v46, v54, v109, v46
	v_mul_f32_e32 v109, 0x3d372713, v46
	v_mul_f32_e32 v109, v46, v109
	v_fma_f32 v109, v46, v109, v46
	v_mul_f32_e32 v109, 0x3f4c422a, v109
	v_add_f32_e32 v109, v109, v109
	v_mul_f32_e32 v109, 0x3fb8aa3b, v109
	v_exp_f32_e32 v109, v109
	v_mul_f32_e32 v46, 0.5, v46
	v_add_f32_e32 v109, 1.0, v109
	v_div_scale_f32 v112, s[2:3], v109, v109, 2.0
	v_rcp_f32_e32 v113, v112
	s_nop 0
	v_fma_f32 v114, -v112, v113, 1.0
	v_fmac_f32_e32 v113, v114, v113
	v_div_scale_f32 v114, vcc, 2.0, v109, 2.0
	v_mul_f32_e32 v115, v114, v113
	v_fma_f32 v116, -v112, v115, v114
	v_fmac_f32_e32 v115, v116, v113
	v_fma_f32 v112, -v112, v115, v114
	v_div_fmas_f32 v112, v112, v113, v115
	v_div_fixup_f32 v109, v112, v109, 2.0
	v_sub_f32_e32 v109, 1.0, v109
	v_add_f32_e32 v109, 1.0, v109
	v_mul_f32_e32 v46, v46, v109
	v_bfe_u32 v109, v46, 16, 1
	v_add3_u32 v46, v46, v109, s31
	global_store_short_d16_hi v[110:111], v46, off
	v_or_b32_e32 v110, 1, v82
	v_mov_b32_e32 v111, v83
	v_lshlrev_b64 v[110:111], 9, v[110:111]
	v_lshl_add_u64 v[110:111], v[110:111], 0, v[50:51]
	v_lshlrev_b64 v[110:111], 1, v[110:111]
	v_lshl_add_u64 v[112:113], s[8:9], 0, v[110:111]
	s_waitcnt vmcnt(3)
	v_lshlrev_b32_e32 v46, 16, v201
	v_fmac_f32_e32 v47, v54, v46
	v_mul_f32_e32 v46, 0x3d372713, v47
	v_mul_f32_e32 v46, v47, v46
	v_fma_f32 v46, v47, v46, v47
	v_mul_f32_e32 v46, 0x3f4c422a, v46
	v_add_f32_e32 v46, v46, v46
	v_mul_f32_e32 v46, 0x3fb8aa3b, v46
	v_exp_f32_e32 v46, v46
	v_mul_f32_e32 v47, 0.5, v47
	v_add_f32_e32 v46, 1.0, v46
	v_div_scale_f32 v109, s[2:3], v46, v46, 2.0
	v_rcp_f32_e32 v112, v109
	s_nop 0
	v_fma_f32 v113, -v109, v112, 1.0
	v_fmac_f32_e32 v112, v113, v112
	v_div_scale_f32 v113, vcc, 2.0, v46, 2.0
	v_mul_f32_e32 v114, v113, v112
	v_fma_f32 v115, -v109, v114, v113
	v_fmac_f32_e32 v114, v115, v112
	v_fma_f32 v109, -v109, v114, v113
	v_div_fmas_f32 v109, v109, v112, v114
	v_div_fixup_f32 v46, v109, v46, 2.0
	v_sub_f32_e32 v46, 1.0, v46
	v_add_f32_e32 v46, 1.0, v46
	v_mul_f32_e32 v46, v47, v46
	v_bfe_u32 v47, v46, 16, 1
	v_add3_u32 v109, v46, v47, s31
	v_lshl_add_u64 v[46:47], s[28:29], 0, v[110:111]
	global_store_short_d16_hi v[46:47], v109, off
	v_or_b32_e32 v46, 2, v82
	v_mov_b32_e32 v47, v83
	v_lshlrev_b64 v[46:47], 9, v[46:47]
	v_lshl_add_u64 v[46:47], v[46:47], 0, v[50:51]
	v_lshlrev_b64 v[46:47], 1, v[46:47]
	v_lshl_add_u64 v[110:111], s[8:9], 0, v[46:47]
	v_lshl_add_u64 v[46:47], s[28:29], 0, v[46:47]
	s_waitcnt vmcnt(3)
	v_lshlrev_b32_e32 v109, 16, v202
	v_fma_f32 v48, v54, v109, v48
	v_mul_f32_e32 v109, 0x3d372713, v48
	v_mul_f32_e32 v109, v48, v109
	v_fma_f32 v109, v48, v109, v48
	v_mul_f32_e32 v109, 0x3f4c422a, v109
	v_add_f32_e32 v109, v109, v109
	v_mul_f32_e32 v109, 0x3fb8aa3b, v109
	v_exp_f32_e32 v109, v109
	v_mul_f32_e32 v48, 0.5, v48
	v_add_f32_e32 v109, 1.0, v109
	v_div_scale_f32 v110, s[2:3], v109, v109, 2.0
	v_rcp_f32_e32 v111, v110
	s_nop 0
	v_fma_f32 v112, -v110, v111, 1.0
	v_fmac_f32_e32 v111, v112, v111
	v_div_scale_f32 v112, vcc, 2.0, v109, 2.0
	v_mul_f32_e32 v113, v112, v111
	v_fma_f32 v114, -v110, v113, v112
	v_fmac_f32_e32 v113, v114, v111
	v_fma_f32 v110, -v110, v113, v112
	v_div_fmas_f32 v110, v110, v111, v113
	v_div_fixup_f32 v109, v110, v109, 2.0
	v_sub_f32_e32 v109, 1.0, v109
	v_add_f32_e32 v109, 1.0, v109
	v_mul_f32_e32 v48, v48, v109
	v_bfe_u32 v109, v48, 16, 1
	v_add3_u32 v48, v48, v109, s31
	global_store_short_d16_hi v[46:47], v48, off
	v_or_b32_e32 v46, 3, v82
	v_mov_b32_e32 v47, v83
	v_lshlrev_b64 v[46:47], 9, v[46:47]
	v_lshl_add_u64 v[46:47], v[46:47], 0, v[50:51]
	v_lshlrev_b64 v[46:47], 1, v[46:47]
	v_lshl_add_u64 v[110:111], s[8:9], 0, v[46:47]
	v_lshl_add_u64 v[46:47], s[28:29], 0, v[46:47]
	v_mfma_f32_16x16x32_bf16 v[114:117], v[42:45], v[30:33], 0
	s_waitcnt vmcnt(3)
	v_lshlrev_b32_e32 v48, 16, v203
	v_fmac_f32_e32 v49, v54, v48
	v_mul_f32_e32 v48, 0x3d372713, v49
	v_mul_f32_e32 v48, v49, v48
	v_fma_f32 v48, v49, v48, v49
	v_mul_f32_e32 v48, 0x3f4c422a, v48
	v_add_f32_e32 v48, v48, v48
	v_mul_f32_e32 v48, 0x3fb8aa3b, v48
	v_exp_f32_e32 v48, v48
	v_mul_f32_e32 v49, 0.5, v49
	v_mov_b32_e32 v123, v114
	v_add_f32_e32 v48, 1.0, v48
	v_div_scale_f32 v109, s[2:3], v48, v48, 2.0
	v_rcp_f32_e32 v110, v109
	s_nop 0
	v_fma_f32 v111, -v109, v110, 1.0
	v_fmac_f32_e32 v110, v111, v110
	v_div_scale_f32 v111, vcc, 2.0, v48, 2.0
	v_mul_f32_e32 v112, v111, v110
	v_fma_f32 v113, -v109, v112, v111
	v_fmac_f32_e32 v112, v113, v110
	v_fma_f32 v109, -v109, v112, v111
	v_div_fmas_f32 v109, v109, v110, v112
	v_div_fixup_f32 v48, v109, v48, 2.0
	v_sub_f32_e32 v48, 1.0, v48
	v_add_f32_e32 v48, 1.0, v48
	v_mul_f32_e32 v48, v49, v48
	v_bfe_u32 v49, v48, 16, 1
	v_add3_u32 v48, v48, v49, s31
	global_store_short_d16_hi v[46:47], v48, off
	v_mfma_f32_16x16x32_bf16 v[46:49], v[42:45], v[26:29], 0
	s_barrier
; __device__ __forceinline__ void s5_bu16(const S5Frag& f, const bf16x8 uf, float* buL, int lane) {
;     const int jj = lane & 15, quad = lane >> 4;
; #pragma unroll
;     for (int nt = 0; nt < 4; ++nt) {
;         const f32x4 z = (f32x4){0.f, 0.f, 0.f, 0.f};
;         const f32x4 dre = __builtin_amdgcn_mfma_f32_16x16x32_bf16(uf, f.bfr[nt], z, 0, 0, 0);
;         const f32x4 dim = __builtin_amdgcn_mfma_f32_16x16x32_bf16(uf, f.bfr[nt + 4], z, 0, 0, 0);
; #pragma unroll
;         for (int r = 0; r < 4; ++r) *(f32x2*)(buL + ((4 * quad + r) * 64 + 16 * nt + jj) * 2) = (f32x2){dre[r], dim[r]};
; __device__ __forceinline__ void s5_pass2_item(PP p, unsigned char* shm, int item, int l) {
;     ...
;         s5_bu16(f, uf[sc], buL, lane);
;         __syncthreads();
; #pragma unroll
;         for (int t = 0; t < 16; ++t) { s5_rec(q, *(const f32x2*)(buL + (t * 64 + lane) * 2), x); xs[t * 132 + lane] = x.x; xs[t * 132 + 64 + lane] = x.y; }
	v_mfma_f32_16x16x32_bf16 v[110:113], v[42:45], v[34:37], 0
	s_nop 5
	v_mov_b32_e32 v118, v46
	s_nop 0
	v_mov_b32_e32 v119, v110
	v_mov_b32_e32 v110, v47
	v_mov_b32_e32 v120, v48
	v_mov_b32_e32 v121, v112
	v_mov_b32_e32 v112, v49
	v_mfma_f32_16x16x32_bf16 v[46:49], v[42:45], v[22:25], 0
	s_nop 7
	v_mov_b32_e32 v122, v46
	v_mov_b32_e32 v114, v47
	v_mov_b32_e32 v46, v48
	v_mov_b32_e32 v47, v116
	ds_write2_b64 v108, v[118:119], v[122:123] offset1:16
	ds_write2_b64 v108, v[120:121], v[46:47] offset0:128 offset1:144
	v_mov_b32_e32 v116, v49
	v_mfma_f32_16x16x32_bf16 v[46:49], v[42:45], v[18:21], 0
	v_mfma_f32_16x16x32_bf16 v[118:121], v[42:45], v[14:17], 0
	s_nop 6
	v_mov_b32_e32 v122, v46
	v_mov_b32_e32 v123, v118
	v_mov_b32_e32 v118, v47
	v_mov_b32_e32 v46, v48
	v_mov_b32_e32 v47, v120
	ds_write2_b64 v108, v[46:47], v[112:113] offset0:160 offset1:192
	v_mov_b32_e32 v120, v49
	v_mfma_f32_16x16x32_bf16 v[46:49], v[42:45], v[10:13], 0
	ds_write2_b64 v108, v[122:123], v[110:111] offset0:32 offset1:64
	ds_write2_b64 v108, v[114:115], v[118:119] offset0:80 offset1:96
	ds_write2_b64 v108, v[116:117], v[120:121] offset0:208 offset1:224
	v_mfma_f32_16x16x32_bf16 v[42:45], v[42:45], v[6:9], 0
	s_nop 3
	v_mov_b32_e32 v110, v46
	s_nop 2
	v_mov_b32_e32 v111, v42
	v_mov_b32_e32 v42, v47
	ds_write2st64_b64 v99, v[110:111], v[42:43] offset0:8 offset1:9
	v_mov_b32_e32 v42, v48
	v_mov_b32_e32 v43, v44
	v_mov_b32_e32 v44, v49
	ds_write2st64_b64 v99, v[42:43], v[44:45] offset0:10 offset1:11
	s_waitcnt lgkmcnt(0)
	s_barrier
	ds_read_b64 v[42:43], v90 offset:4096
	v_xor_b32_e32 v44, 0x80000000, v53
	v_mov_b32_e32 v45, v52
	v_pk_mul_f32 v[44:45], v[0:1], v[44:45] op_sel_hi:[0,1]
	v_pk_fma_f32 v[44:45], v[84:85], v[52:53], v[44:45] op_sel_hi:[0,1,1]
	s_waitcnt lgkmcnt(0)
	v_pk_add_f32 v[42:43], v[44:45], v[42:43]
	ds_write2st64_b32 v98, v42, v43 offset1:1
	ds_read_b64 v[44:45], v90 offset:4608
	v_xor_b32_e32 v46, 0x80000000, v43
	v_mov_b32_e32 v47, v42
	v_pk_mul_f32 v[46:47], v[0:1], v[46:47] op_sel_hi:[0,1]
	v_pk_fma_f32 v[42:43], v[84:85], v[42:43], v[46:47] op_sel_hi:[0,1,1]
	s_waitcnt lgkmcnt(0)
	v_pk_add_f32 v[42:43], v[44:45], v[42:43]
	ds_write2_b32 v98, v42, v43 offset0:132 offset1:196
	ds_read_b64 v[44:45], v90 offset:5120
	v_xor_b32_e32 v46, 0x80000000, v43
	v_mov_b32_e32 v47, v42
	v_pk_mul_f32 v[46:47], v[0:1], v[46:47] op_sel_hi:[0,1]
	v_pk_fma_f32 v[42:43], v[84:85], v[42:43], v[46:47] op_sel_hi:[0,1,1]
	s_waitcnt lgkmcnt(0)
	v_pk_add_f32 v[42:43], v[44:45], v[42:43]
	ds_write2st64_b32 v78, v42, v43 offset0:4 offset1:5
	ds_read_b64 v[44:45], v90 offset:5632
	v_xor_b32_e32 v46, 0x80000000, v43
	v_mov_b32_e32 v47, v42
	v_pk_mul_f32 v[46:47], v[0:1], v[46:47] op_sel_hi:[0,1]
	v_pk_fma_f32 v[42:43], v[84:85], v[42:43], v[46:47] op_sel_hi:[0,1,1]
	s_waitcnt lgkmcnt(0)
	v_pk_add_f32 v[42:43], v[44:45], v[42:43]
	ds_write2st64_b32 v79, v42, v43 offset0:6 offset1:7
	ds_read_b64 v[44:45], v90 offset:6144
	v_xor_b32_e32 v46, 0x80000000, v43
	v_mov_b32_e32 v47, v42
	v_pk_mul_f32 v[46:47], v[0:1], v[46:47] op_sel_hi:[0,1]
	v_pk_fma_f32 v[42:43], v[84:85], v[42:43], v[46:47] op_sel_hi:[0,1,1]
	s_waitcnt lgkmcnt(0)
	v_pk_add_f32 v[42:43], v[44:45], v[42:43]
	ds_write2st64_b32 v80, v42, v43 offset0:8 offset1:9
	ds_read_b64 v[44:45], v90 offset:6656
	v_xor_b32_e32 v46, 0x80000000, v43
	v_mov_b32_e32 v47, v42
	v_pk_mul_f32 v[46:47], v[0:1], v[46:47] op_sel_hi:[0,1]
	v_pk_fma_f32 v[42:43], v[84:85], v[42:43], v[46:47] op_sel_hi:[0,1,1]
	s_waitcnt lgkmcnt(0)
	v_pk_add_f32 v[42:43], v[44:45], v[42:43]
	ds_write2st64_b32 v81, v42, v43 offset0:10 offset1:11
	ds_read_b64 v[44:45], v90 offset:7168
	v_xor_b32_e32 v46, 0x80000000, v43
	v_mov_b32_e32 v47, v42
	v_pk_mul_f32 v[46:47], v[0:1], v[46:47] op_sel_hi:[0,1]
	v_pk_fma_f32 v[42:43], v[84:85], v[42:43], v[46:47] op_sel_hi:[0,1,1]
	s_waitcnt lgkmcnt(0)
	v_pk_add_f32 v[42:43], v[44:45], v[42:43]
	ds_write2st64_b32 v86, v42, v43 offset0:12 offset1:13
	ds_read_b64 v[44:45], v90 offset:7680
	v_xor_b32_e32 v46, 0x80000000, v43
	v_mov_b32_e32 v47, v42
	v_pk_mul_f32 v[46:47], v[0:1], v[46:47] op_sel_hi:[0,1]
	v_pk_fma_f32 v[42:43], v[84:85], v[42:43], v[46:47] op_sel_hi:[0,1,1]
	s_waitcnt lgkmcnt(0)
	v_pk_add_f32 v[42:43], v[44:45], v[42:43]
	ds_write2st64_b32 v87, v42, v43 offset0:14 offset1:15
	ds_read_b64 v[44:45], v90 offset:8192
	v_xor_b32_e32 v46, 0x80000000, v43
	v_mov_b32_e32 v47, v42
	v_pk_mul_f32 v[46:47], v[0:1], v[46:47] op_sel_hi:[0,1]
	v_pk_fma_f32 v[42:43], v[84:85], v[42:43], v[46:47] op_sel_hi:[0,1,1]
	s_waitcnt lgkmcnt(0)
	v_pk_add_f32 v[42:43], v[44:45], v[42:43]
	ds_write2st64_b32 v100, v42, v43 offset0:16 offset1:17
	ds_read_b64 v[44:45], v90 offset:8704
	v_xor_b32_e32 v46, 0x80000000, v43
	v_mov_b32_e32 v47, v42
	v_pk_mul_f32 v[46:47], v[0:1], v[46:47] op_sel_hi:[0,1]
	v_pk_fma_f32 v[42:43], v[84:85], v[42:43], v[46:47] op_sel_hi:[0,1,1]
	s_waitcnt lgkmcnt(0)
	v_pk_add_f32 v[42:43], v[44:45], v[42:43]
	ds_write2st64_b32 v101, v42, v43 offset0:18 offset1:19
	ds_read_b64 v[44:45], v90 offset:9216
	v_xor_b32_e32 v46, 0x80000000, v43
	v_mov_b32_e32 v47, v42
	v_pk_mul_f32 v[46:47], v[0:1], v[46:47] op_sel_hi:[0,1]
	v_pk_fma_f32 v[42:43], v[84:85], v[42:43], v[46:47] op_sel_hi:[0,1,1]
	s_waitcnt lgkmcnt(0)
	v_pk_add_f32 v[42:43], v[44:45], v[42:43]
	ds_write2st64_b32 v102, v42, v43 offset0:20 offset1:21
	ds_read_b64 v[44:45], v90 offset:9728
	v_xor_b32_e32 v46, 0x80000000, v43
	v_mov_b32_e32 v47, v42
	v_pk_mul_f32 v[46:47], v[0:1], v[46:47] op_sel_hi:[0,1]
	v_pk_fma_f32 v[42:43], v[84:85], v[42:43], v[46:47] op_sel_hi:[0,1,1]
	s_waitcnt lgkmcnt(0)
; __device__ __forceinline__ float bf2f(bf16_t v) { return __uint_as_float(((unsigned)v) << 16); }
; __device__ __forceinline__ bf16_t f2bf(float f) { unsigned u = __float_as_uint(f); u += 0x7FFFu + ((u >> 16) & 1u); return (bf16_t)(u >> 16); }
; __device__ __forceinline__ void s5_pass2_item(PP p, unsigned char* shm, int item, int l) {
;     ...
;         for (int t = 0; t < 16; ++t) { s5_rec(q, *(const f32x2*)(buL + (t * 64 + lane) * 2), x); xs[t * 132 + lane] = x.x; xs[t * 132 + 64 + lane] = x.y; }
;         __syncthreads();
;         f32x4 y0 = (f32x4){0.f, 0.f, 0.f, 0.f}, y1 = y0;
;         const f32x4* xrow = (const f32x4*)(xs + cc * 132 + quad * 32);
; #pragma unroll
;         for (int i = 0; i < 8; ++i) { const f32x4 xv = xrow[i];
;             y0 = __builtin_amdgcn_mfma_f32_16x16x4f32(xv[0], cmr[4 * i + 0], y0, 0, 0, 0);
;             y1 = __builtin_amdgcn_mfma_f32_16x16x4f32(xv[1], cmr[4 * i + 1], y1, 0, 0, 0);
;             y0 = __builtin_amdgcn_mfma_f32_16x16x4f32(xv[2], cmr[4 * i + 2], y0, 0, 0, 0);
;             y1 = __builtin_amdgcn_mfma_f32_16x16x4f32(xv[3], cmr[4 * i + 3], y1, 0, 0, 0); }
;         const f32x4 y = y0 + y1;
; #pragma unroll
;         for (int r = 0; r < 4; ++r) { const int tl = sc * 16 + quad * 4 + r;
;             const float v = y[r] + dsk * bf2f(proj[PJ_UA + (row0 + tl) * 512 + g * 16 + cc]);
;             const float z = 0.7978845608028654f * (v + 0.044715f * v * v * v);
;             const float th = 1.0f - 2.0f / (__expf(2.0f * z) + 1.0f);
;             Gout[(row0 + tl) * 512 + g * 16 + cc] = f2bf(0.5f * v * (1.0f + th)); }
	v_pk_add_f32 v[42:43], v[44:45], v[42:43]
	ds_write2st64_b32 v103, v42, v43 offset0:22 offset1:23
	ds_read_b64 v[44:45], v90 offset:10240
	v_xor_b32_e32 v46, 0x80000000, v43
	v_mov_b32_e32 v47, v42
	v_pk_mul_f32 v[46:47], v[0:1], v[46:47] op_sel_hi:[0,1]
	v_pk_fma_f32 v[42:43], v[84:85], v[42:43], v[46:47] op_sel_hi:[0,1,1]
	s_waitcnt lgkmcnt(0)
	v_pk_add_f32 v[42:43], v[44:45], v[42:43]
	ds_write2st64_b32 v104, v42, v43 offset0:24 offset1:25
	ds_read_b64 v[44:45], v90 offset:10752
	v_xor_b32_e32 v46, 0x80000000, v43
	v_mov_b32_e32 v47, v42
	v_pk_mul_f32 v[46:47], v[0:1], v[46:47] op_sel_hi:[0,1]
	v_pk_fma_f32 v[42:43], v[84:85], v[42:43], v[46:47] op_sel_hi:[0,1,1]
	s_waitcnt lgkmcnt(0)
	v_pk_add_f32 v[42:43], v[44:45], v[42:43]
	ds_write2st64_b32 v105, v42, v43 offset0:26 offset1:27
	ds_read_b64 v[44:45], v90 offset:11264
	v_xor_b32_e32 v46, 0x80000000, v43
	v_mov_b32_e32 v47, v42
	v_pk_mul_f32 v[46:47], v[0:1], v[46:47] op_sel_hi:[0,1]
	v_pk_fma_f32 v[42:43], v[84:85], v[42:43], v[46:47] op_sel_hi:[0,1,1]
	s_waitcnt lgkmcnt(0)
	v_pk_add_f32 v[42:43], v[44:45], v[42:43]
	ds_write2st64_b32 v106, v42, v43 offset0:28 offset1:29
	ds_read_b64 v[44:45], v90 offset:11776
	v_xor_b32_e32 v46, 0x80000000, v43
	v_mov_b32_e32 v47, v42
	v_pk_mul_f32 v[46:47], v[0:1], v[46:47] op_sel_hi:[0,1]
	v_pk_fma_f32 v[42:43], v[84:85], v[42:43], v[46:47] op_sel_hi:[0,1,1]
	s_waitcnt lgkmcnt(0)
	v_pk_add_f32 v[46:47], v[44:45], v[42:43]
	ds_write2st64_b32 v107, v46, v47 offset0:30 offset1:31
	s_waitcnt lgkmcnt(0)
	s_barrier
	v_or_b32_e32 v216, 16, v82
	v_mov_b32_e32 v217, v83
	v_lshlrev_b64 v[216:217], 9, v[216:217]
	v_lshl_add_u64 v[216:217], v[216:217], 0, v[50:51]
	v_lshlrev_b64 v[216:217], 1, v[216:217]
	v_lshl_add_u64 v[216:217], s[8:9], 0, v[216:217]
	global_load_ushort v204, v[216:217], off
	global_load_ushort v205, v[216:217], off offset:1024
	global_load_ushort v206, v[216:217], off offset:2048
	global_load_ushort v207, v[216:217], off offset:3072
	ds_read_b128 v[42:45], v89
	ds_read_b128 v[110:113], v89 offset:16
	ds_read_b128 v[114:117], v89 offset:32
	ds_read_b128 v[118:121], v89 offset:48
	s_waitcnt lgkmcnt(3)
	v_mfma_f32_16x16x4_f32 v[122:125], v42, v97, 0
	v_or_b32_e32 v48, 16, v82
	v_mov_b32_e32 v49, v83
	v_lshlrev_b64 v[48:49], 9, v[48:49]
	v_lshl_add_u64 v[48:49], v[48:49], 0, v[50:51]
	v_lshlrev_b64 v[48:49], 1, v[48:49]
	v_lshl_add_u64 v[52:53], s[8:9], 0, v[48:49]
	v_mfma_f32_16x16x4_f32 v[126:129], v43, v96, 0
	v_lshl_add_u64 v[48:49], s[28:29], 0, v[48:49]
	s_waitcnt vmcnt(3)
	v_lshlrev_b32_e32 v52, 16, v204
	v_mfma_f32_16x16x4_f32 v[122:125], v44, v95, v[122:125]
	v_mfma_f32_16x16x4_f32 v[42:45], v45, v94, v[126:129]
	s_waitcnt lgkmcnt(2)
	v_mfma_f32_16x16x4_f32 v[122:125], v110, v93, v[122:125]
	v_mfma_f32_16x16x4_f32 v[42:45], v111, v92, v[42:45]
	v_mfma_f32_16x16x4_f32 v[122:125], v112, v91, v[122:125]
	v_mfma_f32_16x16x4_f32 v[42:45], v113, v88, v[42:45]
	s_waitcnt lgkmcnt(1)
	v_mfma_f32_16x16x4_f32 v[110:113], v114, v85, v[122:125]
	v_mfma_f32_16x16x4_f32 v[42:45], v115, v55, v[42:45]
	v_mfma_f32_16x16x4_f32 v[110:113], v116, v56, v[110:113]
	v_mfma_f32_16x16x4_f32 v[42:45], v117, v57, v[42:45]
	ds_read_b128 v[114:117], v89 offset:64
	s_waitcnt lgkmcnt(1)
	v_mfma_f32_16x16x4_f32 v[110:113], v118, v58, v[110:113]
	v_mfma_f32_16x16x4_f32 v[42:45], v119, v59, v[42:45]
	v_mfma_f32_16x16x4_f32 v[110:113], v120, v60, v[110:113]
	v_mfma_f32_16x16x4_f32 v[42:45], v121, v61, v[42:45]
	s_waitcnt lgkmcnt(0)
	v_mfma_f32_16x16x4_f32 v[110:113], v114, v62, v[110:113]
	v_mfma_f32_16x16x4_f32 v[42:45], v115, v63, v[42:45]
	v_mfma_f32_16x16x4_f32 v[110:113], v116, v64, v[110:113]
	v_mfma_f32_16x16x4_f32 v[42:45], v117, v65, v[42:45]
	ds_read_b128 v[114:117], v89 offset:80
	s_waitcnt lgkmcnt(0)
	v_mfma_f32_16x16x4_f32 v[110:113], v114, v66, v[110:113]
	v_mfma_f32_16x16x4_f32 v[42:45], v115, v67, v[42:45]
	v_mfma_f32_16x16x4_f32 v[110:113], v116, v68, v[110:113]
	v_mfma_f32_16x16x4_f32 v[42:45], v117, v69, v[42:45]
	ds_read_b128 v[114:117], v89 offset:96
	s_waitcnt lgkmcnt(0)
	v_mfma_f32_16x16x4_f32 v[110:113], v114, v70, v[110:113]
	v_mfma_f32_16x16x4_f32 v[42:45], v115, v71, v[42:45]
	v_mfma_f32_16x16x4_f32 v[110:113], v116, v72, v[110:113]
	v_mfma_f32_16x16x4_f32 v[42:45], v117, v73, v[42:45]
	ds_read_b128 v[114:117], v89 offset:112
	s_waitcnt lgkmcnt(0)
	v_mfma_f32_16x16x4_f32 v[110:113], v114, v74, v[110:113]
	v_mfma_f32_16x16x4_f32 v[42:45], v115, v75, v[42:45]
	v_mfma_f32_16x16x4_f32 v[110:113], v116, v76, v[110:113]
	v_mfma_f32_16x16x4_f32 v[42:45], v117, v77, v[42:45]
	v_mfma_f32_16x16x32_bf16 v[114:117], v[38:41], v[30:33], 0
	s_nop 8
	v_add_f32_e64 v42, v110, v42
	v_add_f32_e64 v43, v111, v43
	v_pk_add_f32 v[44:45], v[112:113], v[44:45]
	v_fma_f32 v42, v54, v52, v42
	v_mul_f32_e32 v52, 0x3d372713, v42
	v_mul_f32_e32 v52, v42, v52
	v_fma_f32 v52, v42, v52, v42
	v_mul_f32_e32 v52, 0x3f4c422a, v52
	v_add_f32_e32 v52, v52, v52
	v_mul_f32_e32 v52, 0x3fb8aa3b, v52
	v_exp_f32_e32 v52, v52
	v_mul_f32_e32 v42, 0.5, v42
	v_mov_b32_e32 v119, v114
	v_mfma_f32_16x16x32_bf16 v[30:33], v[2:5], v[30:33], 0
	v_add_f32_e32 v52, 1.0, v52
	v_div_scale_f32 v53, s[2:3], v52, v52, 2.0
	v_rcp_f32_e32 v109, v53
	s_nop 0
	v_fma_f32 v110, -v53, v109, 1.0
	v_fmac_f32_e32 v109, v110, v109
	v_div_scale_f32 v110, vcc, 2.0, v52, 2.0
	v_mul_f32_e32 v111, v110, v109
	v_fma_f32 v112, -v53, v111, v110
	v_fmac_f32_e32 v111, v112, v109
	v_fma_f32 v53, -v53, v111, v110
	v_div_fmas_f32 v53, v53, v109, v111
	v_div_fixup_f32 v52, v53, v52, 2.0
	v_sub_f32_e32 v52, 1.0, v52
	v_add_f32_e32 v52, 1.0, v52
	v_mul_f32_e32 v42, v42, v52
	v_bfe_u32 v52, v42, 16, 1
	v_add3_u32 v42, v42, v52, s31
	global_store_short_d16_hi v[48:49], v42, off
	v_or_b32_e32 v48, 17, v82
	v_mov_b32_e32 v49, v83
	v_lshlrev_b64 v[48:49], 9, v[48:49]
	v_lshl_add_u64 v[48:49], v[48:49], 0, v[50:51]
	v_lshlrev_b64 v[48:49], 1, v[48:49]
	v_lshl_add_u64 v[52:53], s[8:9], 0, v[48:49]
	s_waitcnt vmcnt(3)
; __device__ __forceinline__ float bf2f(bf16_t v) { return __uint_as_float(((unsigned)v) << 16); }
; __device__ __forceinline__ bf16_t f2bf(float f) { unsigned u = __float_as_uint(f); u += 0x7FFFu + ((u >> 16) & 1u); return (bf16_t)(u >> 16); }
; __device__ __forceinline__ void s5_bu16(const S5Frag& f, const bf16x8 uf, float* buL, int lane) {
;     const int jj = lane & 15, quad = lane >> 4;
; #pragma unroll
;     for (int nt = 0; nt < 4; ++nt) {
;         const f32x4 z = (f32x4){0.f, 0.f, 0.f, 0.f};
;         const f32x4 dre = __builtin_amdgcn_mfma_f32_16x16x32_bf16(uf, f.bfr[nt], z, 0, 0, 0);
;         const f32x4 dim = __builtin_amdgcn_mfma_f32_16x16x32_bf16(uf, f.bfr[nt + 4], z, 0, 0, 0);
; #pragma unroll
;         for (int r = 0; r < 4; ++r) *(f32x2*)(buL + ((4 * quad + r) * 64 + 16 * nt + jj) * 2) = (f32x2){dre[r], dim[r]};
; __device__ __forceinline__ void s5_pass2_item(PP p, unsigned char* shm, int item, int l) {
;     ...
;         for (int r = 0; r < 4; ++r) { const int tl = sc * 16 + quad * 4 + r;
;             const float v = y[r] + dsk * bf2f(proj[PJ_UA + (row0 + tl) * 512 + g * 16 + cc]);
;             const float z = 0.7978845608028654f * (v + 0.044715f * v * v * v);
;             const float th = 1.0f - 2.0f / (__expf(2.0f * z) + 1.0f);
;             Gout[(row0 + tl) * 512 + g * 16 + cc] = f2bf(0.5f * v * (1.0f + th)); }
	v_lshlrev_b32_e32 v42, 16, v205
	v_fmac_f32_e32 v43, v54, v42
	v_mul_f32_e32 v42, 0x3d372713, v43
	v_mul_f32_e32 v42, v43, v42
	v_fma_f32 v42, v43, v42, v43
	v_mul_f32_e32 v42, 0x3f4c422a, v42
	v_add_f32_e32 v42, v42, v42
	v_mul_f32_e32 v42, 0x3fb8aa3b, v42
	v_exp_f32_e32 v42, v42
	v_mul_f32_e32 v43, 0.5, v43
	v_add_f32_e32 v42, 1.0, v42
	v_div_scale_f32 v52, s[2:3], v42, v42, 2.0
	v_rcp_f32_e32 v53, v52
	s_nop 0
	v_fma_f32 v109, -v52, v53, 1.0
	v_fmac_f32_e32 v53, v109, v53
	v_div_scale_f32 v109, vcc, 2.0, v42, 2.0
	v_mul_f32_e32 v110, v109, v53
	v_fma_f32 v111, -v52, v110, v109
	v_fmac_f32_e32 v110, v111, v53
	v_fma_f32 v52, -v52, v110, v109
	v_div_fmas_f32 v52, v52, v53, v110
	v_div_fixup_f32 v42, v52, v42, 2.0
	v_sub_f32_e32 v42, 1.0, v42
	v_add_f32_e32 v42, 1.0, v42
	v_mul_f32_e32 v42, v43, v42
	v_bfe_u32 v43, v42, 16, 1
	v_add3_u32 v52, v42, v43, s31
	v_lshl_add_u64 v[42:43], s[28:29], 0, v[48:49]
	global_store_short_d16_hi v[42:43], v52, off
	v_or_b32_e32 v42, 18, v82
	v_mov_b32_e32 v43, v83
	v_lshlrev_b64 v[42:43], 9, v[42:43]
	v_lshl_add_u64 v[42:43], v[42:43], 0, v[50:51]
	v_lshlrev_b64 v[42:43], 1, v[42:43]
	v_lshl_add_u64 v[48:49], s[8:9], 0, v[42:43]
	v_lshl_add_u64 v[42:43], s[28:29], 0, v[42:43]
	s_waitcnt vmcnt(3)
	v_lshlrev_b32_e32 v48, 16, v206
	v_fma_f32 v44, v54, v48, v44
	v_mul_f32_e32 v48, 0x3d372713, v44
	v_mul_f32_e32 v48, v44, v48
	v_fma_f32 v48, v44, v48, v44
	v_mul_f32_e32 v48, 0x3f4c422a, v48
	v_add_f32_e32 v48, v48, v48
	v_mul_f32_e32 v48, 0x3fb8aa3b, v48
	v_exp_f32_e32 v48, v48
	v_mul_f32_e32 v44, 0.5, v44
	v_add_f32_e32 v48, 1.0, v48
	v_div_scale_f32 v49, s[2:3], v48, v48, 2.0
	v_rcp_f32_e32 v52, v49
	s_nop 0
	v_fma_f32 v53, -v49, v52, 1.0
	v_fmac_f32_e32 v52, v53, v52
	v_div_scale_f32 v53, vcc, 2.0, v48, 2.0
	v_mul_f32_e32 v109, v53, v52
	v_fma_f32 v110, -v49, v109, v53
	v_fmac_f32_e32 v109, v110, v52
	v_fma_f32 v49, -v49, v109, v53
	v_div_fmas_f32 v49, v49, v52, v109
	v_div_fixup_f32 v48, v49, v48, 2.0
	v_sub_f32_e32 v48, 1.0, v48
	v_add_f32_e32 v48, 1.0, v48
	v_mul_f32_e32 v44, v44, v48
	v_bfe_u32 v48, v44, 16, 1
	v_add3_u32 v44, v44, v48, s31
	global_store_short_d16_hi v[42:43], v44, off
	v_or_b32_e32 v42, 19, v82
	v_mov_b32_e32 v43, v83
	v_lshlrev_b64 v[42:43], 9, v[42:43]
	v_lshl_add_u64 v[42:43], v[42:43], 0, v[50:51]
	v_lshlrev_b64 v[42:43], 1, v[42:43]
	v_lshl_add_u64 v[48:49], s[8:9], 0, v[42:43]
	v_lshl_add_u64 v[42:43], s[28:29], 0, v[42:43]
	v_mfma_f32_16x16x32_bf16 v[110:113], v[38:41], v[26:29], 0
	s_waitcnt vmcnt(3)
	v_lshlrev_b32_e32 v44, 16, v207
	v_fmac_f32_e32 v45, v54, v44
	v_mul_f32_e32 v44, 0x3d372713, v45
	v_mul_f32_e32 v44, v45, v44
	v_fma_f32 v44, v45, v44, v45
	v_mul_f32_e32 v44, 0x3f4c422a, v44
	v_add_f32_e32 v44, v44, v44
	v_mul_f32_e32 v44, 0x3fb8aa3b, v44
	v_exp_f32_e32 v44, v44
	v_mul_f32_e32 v45, 0.5, v45
	v_add_f32_e32 v44, 1.0, v44
	v_div_scale_f32 v48, s[2:3], v44, v44, 2.0
	v_rcp_f32_e32 v49, v48
	s_nop 0
	v_fma_f32 v52, -v48, v49, 1.0
	v_fmac_f32_e32 v49, v52, v49
	v_div_scale_f32 v52, vcc, 2.0, v44, 2.0
	v_mul_f32_e32 v53, v52, v49
	v_fma_f32 v109, -v48, v53, v52
	v_fmac_f32_e32 v53, v109, v49
	v_fma_f32 v48, -v48, v53, v52
	v_div_fmas_f32 v48, v48, v49, v53
	v_div_fixup_f32 v44, v48, v44, 2.0
	v_sub_f32_e32 v44, 1.0, v44
	v_add_f32_e32 v44, 1.0, v44
	v_mul_f32_e32 v44, v45, v44
	v_bfe_u32 v45, v44, 16, 1
	v_add3_u32 v44, v44, v45, s31
	global_store_short_d16_hi v[42:43], v44, off
	v_mfma_f32_16x16x32_bf16 v[42:45], v[38:41], v[34:37], 0
	v_mov_b32_e32 v48, v110
	v_mov_b32_e32 v52, v112
	s_barrier
	s_nop 4
	v_mov_b32_e32 v49, v42
	v_mov_b32_e32 v42, v111
	v_mov_b32_e32 v53, v44
	v_mov_b32_e32 v44, v113
	v_mfma_f32_16x16x32_bf16 v[110:113], v[38:41], v[22:25], 0
	v_mfma_f32_16x16x32_bf16 v[22:25], v[2:5], v[22:25], 0
	s_nop 6
	v_mov_b32_e32 v118, v110
	ds_write2_b64 v108, v[48:49], v[118:119] offset1:16
	v_mov_b32_e32 v114, v111
	v_mov_b32_e32 v48, v112
	v_mov_b32_e32 v49, v116
	v_mov_b32_e32 v116, v113
	v_mfma_f32_16x16x32_bf16 v[110:113], v[38:41], v[18:21], 0
	ds_write2_b64 v108, v[52:53], v[48:49] offset0:128 offset1:144
	v_mfma_f32_16x16x32_bf16 v[118:121], v[38:41], v[14:17], 0
	v_mfma_f32_16x16x32_bf16 v[18:21], v[2:5], v[18:21], 0
	s_nop 4
	v_mov_b32_e32 v48, v110
	s_nop 0
	v_mov_b32_e32 v49, v118
	ds_write2_b64 v108, v[48:49], v[42:43] offset0:32 offset1:64
	v_mov_b32_e32 v42, v112
	v_mov_b32_e32 v43, v120
	ds_write2_b64 v108, v[42:43], v[44:45] offset0:160 offset1:192
	v_mfma_f32_16x16x32_bf16 v[42:45], v[38:41], v[10:13], 0
	v_mov_b32_e32 v118, v111
	v_mov_b32_e32 v120, v113
	ds_write2_b64 v108, v[114:115], v[118:119] offset0:80 offset1:96
	v_mfma_f32_16x16x32_bf16 v[38:41], v[38:41], v[6:9], 0
	ds_write2_b64 v108, v[116:117], v[120:121] offset0:208 offset1:224
	s_nop 2
	v_mov_b32_e32 v48, v42
	v_mfma_f32_16x16x32_bf16 v[14:17], v[2:5], v[14:17], 0
	v_mfma_f32_16x16x32_bf16 v[10:13], v[2:5], v[10:13], 0
	s_nop 0
	v_mov_b32_e32 v49, v38
	v_mov_b32_e32 v38, v43
	ds_write2st64_b64 v99, v[48:49], v[38:39] offset0:8 offset1:9
	v_mov_b32_e32 v38, v44
	v_mov_b32_e32 v39, v40
	v_mov_b32_e32 v40, v45
	ds_write2st64_b64 v99, v[38:39], v[40:41] offset0:10 offset1:11
	s_waitcnt lgkmcnt(0)
	s_barrier
; __device__ __forceinline__ void s5_pass2_item(PP p, unsigned char* shm, int item, int l) {
;     ...
;         s5_bu16(f, uf[sc], buL, lane);
;         __syncthreads();
; #pragma unroll
;         for (int t = 0; t < 16; ++t) { s5_rec(q, *(const f32x2*)(buL + (t * 64 + lane) * 2), x); xs[t * 132 + lane] = x.x; xs[t * 132 + 64 + lane] = x.y; }
;         __syncthreads();
	ds_read_b64 v[38:39], v90 offset:4096
	v_xor_b32_e32 v40, 0x80000000, v47
	v_mov_b32_e32 v41, v46
	v_pk_mul_f32 v[40:41], v[0:1], v[40:41] op_sel_hi:[0,1]
	v_pk_fma_f32 v[40:41], v[84:85], v[46:47], v[40:41] op_sel_hi:[0,1,1]
	s_waitcnt lgkmcnt(0)
	v_pk_add_f32 v[38:39], v[40:41], v[38:39]
	ds_write2st64_b32 v98, v38, v39 offset1:1
	ds_read_b64 v[40:41], v90 offset:4608
	v_xor_b32_e32 v42, 0x80000000, v39
	v_mov_b32_e32 v43, v38
	v_pk_mul_f32 v[42:43], v[0:1], v[42:43] op_sel_hi:[0,1]
	v_pk_fma_f32 v[38:39], v[84:85], v[38:39], v[42:43] op_sel_hi:[0,1,1]
	s_waitcnt lgkmcnt(0)
	v_pk_add_f32 v[38:39], v[40:41], v[38:39]
	ds_write2_b32 v98, v38, v39 offset0:132 offset1:196
	ds_read_b64 v[40:41], v90 offset:5120
	v_xor_b32_e32 v42, 0x80000000, v39
	v_mov_b32_e32 v43, v38
	v_pk_mul_f32 v[42:43], v[0:1], v[42:43] op_sel_hi:[0,1]
	v_pk_fma_f32 v[38:39], v[84:85], v[38:39], v[42:43] op_sel_hi:[0,1,1]
	s_waitcnt lgkmcnt(0)
	v_pk_add_f32 v[38:39], v[40:41], v[38:39]
	ds_write2st64_b32 v78, v38, v39 offset0:4 offset1:5
	ds_read_b64 v[40:41], v90 offset:5632
	v_xor_b32_e32 v42, 0x80000000, v39
	v_mov_b32_e32 v43, v38
	v_pk_mul_f32 v[42:43], v[0:1], v[42:43] op_sel_hi:[0,1]
	v_pk_fma_f32 v[38:39], v[84:85], v[38:39], v[42:43] op_sel_hi:[0,1,1]
	s_waitcnt lgkmcnt(0)
	v_pk_add_f32 v[38:39], v[40:41], v[38:39]
	ds_write2st64_b32 v79, v38, v39 offset0:6 offset1:7
	ds_read_b64 v[40:41], v90 offset:6144
	v_xor_b32_e32 v42, 0x80000000, v39
	v_mov_b32_e32 v43, v38
	v_pk_mul_f32 v[42:43], v[0:1], v[42:43] op_sel_hi:[0,1]
	v_pk_fma_f32 v[38:39], v[84:85], v[38:39], v[42:43] op_sel_hi:[0,1,1]
	s_waitcnt lgkmcnt(0)
	v_pk_add_f32 v[38:39], v[40:41], v[38:39]
	ds_write2st64_b32 v80, v38, v39 offset0:8 offset1:9
	ds_read_b64 v[40:41], v90 offset:6656
	v_xor_b32_e32 v42, 0x80000000, v39
	v_mov_b32_e32 v43, v38
	v_pk_mul_f32 v[42:43], v[0:1], v[42:43] op_sel_hi:[0,1]
	v_pk_fma_f32 v[38:39], v[84:85], v[38:39], v[42:43] op_sel_hi:[0,1,1]
	s_waitcnt lgkmcnt(0)
	v_pk_add_f32 v[38:39], v[40:41], v[38:39]
	ds_write2st64_b32 v81, v38, v39 offset0:10 offset1:11
	ds_read_b64 v[40:41], v90 offset:7168
	v_xor_b32_e32 v42, 0x80000000, v39
	v_mov_b32_e32 v43, v38
	v_pk_mul_f32 v[42:43], v[0:1], v[42:43] op_sel_hi:[0,1]
	v_pk_fma_f32 v[38:39], v[84:85], v[38:39], v[42:43] op_sel_hi:[0,1,1]
	s_waitcnt lgkmcnt(0)
	v_pk_add_f32 v[38:39], v[40:41], v[38:39]
	ds_write2st64_b32 v86, v38, v39 offset0:12 offset1:13
	ds_read_b64 v[40:41], v90 offset:7680
	v_xor_b32_e32 v42, 0x80000000, v39
	v_mov_b32_e32 v43, v38
	v_pk_mul_f32 v[42:43], v[0:1], v[42:43] op_sel_hi:[0,1]
	v_pk_fma_f32 v[38:39], v[84:85], v[38:39], v[42:43] op_sel_hi:[0,1,1]
	s_waitcnt lgkmcnt(0)
	v_pk_add_f32 v[38:39], v[40:41], v[38:39]
	ds_write2st64_b32 v87, v38, v39 offset0:14 offset1:15
	ds_read_b64 v[40:41], v90 offset:8192
	v_xor_b32_e32 v42, 0x80000000, v39
	v_mov_b32_e32 v43, v38
	v_pk_mul_f32 v[42:43], v[0:1], v[42:43] op_sel_hi:[0,1]
	v_pk_fma_f32 v[38:39], v[84:85], v[38:39], v[42:43] op_sel_hi:[0,1,1]
	s_waitcnt lgkmcnt(0)
	v_pk_add_f32 v[38:39], v[40:41], v[38:39]
	ds_write2st64_b32 v100, v38, v39 offset0:16 offset1:17
	ds_read_b64 v[40:41], v90 offset:8704
	v_xor_b32_e32 v42, 0x80000000, v39
	v_mov_b32_e32 v43, v38
	v_pk_mul_f32 v[42:43], v[0:1], v[42:43] op_sel_hi:[0,1]
	v_pk_fma_f32 v[38:39], v[84:85], v[38:39], v[42:43] op_sel_hi:[0,1,1]
	s_waitcnt lgkmcnt(0)
	v_pk_add_f32 v[38:39], v[40:41], v[38:39]
	ds_write2st64_b32 v101, v38, v39 offset0:18 offset1:19
	ds_read_b64 v[40:41], v90 offset:9216
	v_xor_b32_e32 v42, 0x80000000, v39
	v_mov_b32_e32 v43, v38
	v_pk_mul_f32 v[42:43], v[0:1], v[42:43] op_sel_hi:[0,1]
	v_pk_fma_f32 v[38:39], v[84:85], v[38:39], v[42:43] op_sel_hi:[0,1,1]
	s_waitcnt lgkmcnt(0)
	v_pk_add_f32 v[38:39], v[40:41], v[38:39]
	ds_write2st64_b32 v102, v38, v39 offset0:20 offset1:21
	ds_read_b64 v[40:41], v90 offset:9728
	v_xor_b32_e32 v42, 0x80000000, v39
	v_mov_b32_e32 v43, v38
	v_pk_mul_f32 v[42:43], v[0:1], v[42:43] op_sel_hi:[0,1]
	v_pk_fma_f32 v[38:39], v[84:85], v[38:39], v[42:43] op_sel_hi:[0,1,1]
	s_waitcnt lgkmcnt(0)
	v_pk_add_f32 v[38:39], v[40:41], v[38:39]
	ds_write2st64_b32 v103, v38, v39 offset0:22 offset1:23
	ds_read_b64 v[40:41], v90 offset:10240
	v_xor_b32_e32 v42, 0x80000000, v39
	v_mov_b32_e32 v43, v38
	v_pk_mul_f32 v[42:43], v[0:1], v[42:43] op_sel_hi:[0,1]
	v_pk_fma_f32 v[38:39], v[84:85], v[38:39], v[42:43] op_sel_hi:[0,1,1]
	s_waitcnt lgkmcnt(0)
	v_pk_add_f32 v[38:39], v[40:41], v[38:39]
	ds_write2st64_b32 v104, v38, v39 offset0:24 offset1:25
	ds_read_b64 v[40:41], v90 offset:10752
	v_xor_b32_e32 v42, 0x80000000, v39
	v_mov_b32_e32 v43, v38
	v_pk_mul_f32 v[42:43], v[0:1], v[42:43] op_sel_hi:[0,1]
	v_pk_fma_f32 v[38:39], v[84:85], v[38:39], v[42:43] op_sel_hi:[0,1,1]
	s_waitcnt lgkmcnt(0)
	v_pk_add_f32 v[38:39], v[40:41], v[38:39]
	ds_write2st64_b32 v105, v38, v39 offset0:26 offset1:27
	ds_read_b64 v[40:41], v90 offset:11264
	v_xor_b32_e32 v42, 0x80000000, v39
	v_mov_b32_e32 v43, v38
	v_pk_mul_f32 v[42:43], v[0:1], v[42:43] op_sel_hi:[0,1]
	v_pk_fma_f32 v[38:39], v[84:85], v[38:39], v[42:43] op_sel_hi:[0,1,1]
	s_waitcnt lgkmcnt(0)
	v_pk_add_f32 v[38:39], v[40:41], v[38:39]
	ds_write2st64_b32 v106, v38, v39 offset0:28 offset1:29
	ds_read_b64 v[40:41], v90 offset:11776
	v_xor_b32_e32 v42, 0x80000000, v39
	v_mov_b32_e32 v43, v38
	v_pk_mul_f32 v[42:43], v[0:1], v[42:43] op_sel_hi:[0,1]
	v_pk_fma_f32 v[38:39], v[84:85], v[38:39], v[42:43] op_sel_hi:[0,1,1]
	s_waitcnt lgkmcnt(0)
	v_pk_add_f32 v[38:39], v[40:41], v[38:39]
	ds_write2st64_b32 v107, v38, v39 offset0:30 offset1:31
	s_waitcnt lgkmcnt(0)
	s_barrier
; __device__ __forceinline__ float bf2f(bf16_t v) { return __uint_as_float(((unsigned)v) << 16); }
; __device__ __forceinline__ bf16_t f2bf(float f) { unsigned u = __float_as_uint(f); u += 0x7FFFu + ((u >> 16) & 1u); return (bf16_t)(u >> 16); }
; __device__ __forceinline__ void s5_pass2_item(PP p, unsigned char* shm, int item, int l) {
;     ...
;         f32x4 y0 = (f32x4){0.f, 0.f, 0.f, 0.f}, y1 = y0;
;         const f32x4* xrow = (const f32x4*)(xs + cc * 132 + quad * 32);
; #pragma unroll
;         for (int i = 0; i < 8; ++i) { const f32x4 xv = xrow[i];
;             y0 = __builtin_amdgcn_mfma_f32_16x16x4f32(xv[0], cmr[4 * i + 0], y0, 0, 0, 0);
;             y1 = __builtin_amdgcn_mfma_f32_16x16x4f32(xv[1], cmr[4 * i + 1], y1, 0, 0, 0);
;             y0 = __builtin_amdgcn_mfma_f32_16x16x4f32(xv[2], cmr[4 * i + 2], y0, 0, 0, 0);
;             y1 = __builtin_amdgcn_mfma_f32_16x16x4f32(xv[3], cmr[4 * i + 3], y1, 0, 0, 0); }
;         const f32x4 y = y0 + y1;
; #pragma unroll
;         for (int r = 0; r < 4; ++r) { const int tl = sc * 16 + quad * 4 + r;
;             const float v = y[r] + dsk * bf2f(proj[PJ_UA + (row0 + tl) * 512 + g * 16 + cc]);
;             const float z = 0.7978845608028654f * (v + 0.044715f * v * v * v);
;             const float th = 1.0f - 2.0f / (__expf(2.0f * z) + 1.0f);
;             Gout[(row0 + tl) * 512 + g * 16 + cc] = f2bf(0.5f * v * (1.0f + th)); }
	v_or_b32_e32 v216, 32, v82
	v_mov_b32_e32 v217, v83
	v_lshlrev_b64 v[216:217], 9, v[216:217]
	v_lshl_add_u64 v[216:217], v[216:217], 0, v[50:51]
	v_lshlrev_b64 v[216:217], 1, v[216:217]
	v_lshl_add_u64 v[216:217], s[8:9], 0, v[216:217]
	global_load_ushort v208, v[216:217], off
	global_load_ushort v209, v[216:217], off offset:1024
	global_load_ushort v210, v[216:217], off offset:2048
	global_load_ushort v211, v[216:217], off offset:3072
	ds_read_b128 v[40:43], v89
	ds_read_b128 v[44:47], v89 offset:16
	ds_read_b128 v[110:113], v89 offset:32
	ds_read_b128 v[114:117], v89 offset:48
	s_waitcnt lgkmcnt(3)
	v_mfma_f32_16x16x4_f32 v[118:121], v40, v97, 0
	v_mfma_f32_16x16x4_f32 v[122:125], v41, v96, 0
	v_mfma_f32_16x16x4_f32 v[118:121], v42, v95, v[118:121]
	v_mfma_f32_16x16x4_f32 v[40:43], v43, v94, v[122:125]
	s_waitcnt lgkmcnt(2)
	v_mfma_f32_16x16x4_f32 v[118:121], v44, v93, v[118:121]
	v_mfma_f32_16x16x4_f32 v[40:43], v45, v92, v[40:43]
	v_mfma_f32_16x16x4_f32 v[118:121], v46, v91, v[118:121]
	v_mfma_f32_16x16x4_f32 v[40:43], v47, v88, v[40:43]
	s_waitcnt lgkmcnt(1)
	v_mfma_f32_16x16x4_f32 v[44:47], v110, v85, v[118:121]
	v_mfma_f32_16x16x4_f32 v[40:43], v111, v55, v[40:43]
	v_mfma_f32_16x16x4_f32 v[44:47], v112, v56, v[44:47]
	v_mfma_f32_16x16x4_f32 v[40:43], v113, v57, v[40:43]
	ds_read_b128 v[110:113], v89 offset:64
	s_waitcnt lgkmcnt(1)
	v_mfma_f32_16x16x4_f32 v[44:47], v114, v58, v[44:47]
	v_mfma_f32_16x16x4_f32 v[40:43], v115, v59, v[40:43]
	v_mfma_f32_16x16x4_f32 v[44:47], v116, v60, v[44:47]
	v_mfma_f32_16x16x4_f32 v[40:43], v117, v61, v[40:43]
	s_waitcnt lgkmcnt(0)
	v_mfma_f32_16x16x4_f32 v[44:47], v110, v62, v[44:47]
	v_mfma_f32_16x16x4_f32 v[40:43], v111, v63, v[40:43]
	v_mfma_f32_16x16x4_f32 v[44:47], v112, v64, v[44:47]
	v_mfma_f32_16x16x4_f32 v[40:43], v113, v65, v[40:43]
	ds_read_b128 v[110:113], v89 offset:80
	s_waitcnt lgkmcnt(0)
	v_mfma_f32_16x16x4_f32 v[44:47], v110, v66, v[44:47]
	v_mfma_f32_16x16x4_f32 v[40:43], v111, v67, v[40:43]
	v_mfma_f32_16x16x4_f32 v[44:47], v112, v68, v[44:47]
	v_mfma_f32_16x16x4_f32 v[40:43], v113, v69, v[40:43]
	ds_read_b128 v[110:113], v89 offset:96
	s_waitcnt lgkmcnt(0)
	v_mfma_f32_16x16x4_f32 v[44:47], v110, v70, v[44:47]
	v_mfma_f32_16x16x4_f32 v[40:43], v111, v71, v[40:43]
	v_mfma_f32_16x16x4_f32 v[44:47], v112, v72, v[44:47]
	v_mfma_f32_16x16x4_f32 v[40:43], v113, v73, v[40:43]
	ds_read_b128 v[110:113], v89 offset:112
	s_waitcnt lgkmcnt(0)
	v_mfma_f32_16x16x4_f32 v[44:47], v110, v74, v[44:47]
	v_mfma_f32_16x16x4_f32 v[40:43], v111, v75, v[40:43]
	v_mfma_f32_16x16x4_f32 v[44:47], v112, v76, v[44:47]
	v_mfma_f32_16x16x4_f32 v[40:43], v113, v77, v[40:43]
	s_nop 9
	v_pk_add_f32 v[40:41], v[44:45], v[40:41]
	v_or_b32_e32 v44, 32, v82
	v_mov_b32_e32 v45, v83
	v_lshlrev_b64 v[44:45], 9, v[44:45]
	v_lshl_add_u64 v[44:45], v[44:45], 0, v[50:51]
	v_lshlrev_b64 v[44:45], 1, v[44:45]
	v_pk_add_f32 v[42:43], v[46:47], v[42:43]
	v_lshl_add_u64 v[46:47], s[8:9], 0, v[44:45]
	v_lshl_add_u64 v[44:45], s[28:29], 0, v[44:45]
	s_waitcnt vmcnt(3)
	v_lshlrev_b32_e32 v46, 16, v208
	v_fma_f32 v40, v54, v46, v40
	v_mul_f32_e32 v46, 0x3d372713, v40
	v_mul_f32_e32 v46, v40, v46
	v_fma_f32 v46, v40, v46, v40
	v_mul_f32_e32 v46, 0x3f4c422a, v46
	v_add_f32_e32 v46, v46, v46
	v_mul_f32_e32 v46, 0x3fb8aa3b, v46
	v_exp_f32_e32 v46, v46
	v_mul_f32_e32 v40, 0.5, v40
	v_add_f32_e32 v46, 1.0, v46
	v_div_scale_f32 v47, s[2:3], v46, v46, 2.0
	v_rcp_f32_e32 v48, v47
	s_nop 0
	v_fma_f32 v49, -v47, v48, 1.0
	v_fmac_f32_e32 v48, v49, v48
	v_div_scale_f32 v49, vcc, 2.0, v46, 2.0
	v_mul_f32_e32 v52, v49, v48
	v_fma_f32 v53, -v47, v52, v49
	v_fmac_f32_e32 v52, v53, v48
	v_fma_f32 v47, -v47, v52, v49
	v_div_fmas_f32 v47, v47, v48, v52
	v_div_fixup_f32 v46, v47, v46, 2.0
	v_sub_f32_e32 v46, 1.0, v46
	v_add_f32_e32 v46, 1.0, v46
	v_mul_f32_e32 v40, v40, v46
	v_bfe_u32 v46, v40, 16, 1
	v_add3_u32 v40, v40, v46, s31
	global_store_short_d16_hi v[44:45], v40, off
	v_or_b32_e32 v44, 33, v82
	v_mov_b32_e32 v45, v83
	v_lshlrev_b64 v[44:45], 9, v[44:45]
	v_lshl_add_u64 v[44:45], v[44:45], 0, v[50:51]
	v_lshlrev_b64 v[44:45], 1, v[44:45]
	v_lshl_add_u64 v[46:47], s[8:9], 0, v[44:45]
	s_waitcnt vmcnt(3)
	v_lshlrev_b32_e32 v40, 16, v209
	v_fmac_f32_e32 v41, v54, v40
	v_mul_f32_e32 v40, 0x3d372713, v41
	v_mul_f32_e32 v40, v41, v40
	v_fma_f32 v40, v41, v40, v41
	v_mul_f32_e32 v40, 0x3f4c422a, v40
	v_add_f32_e32 v40, v40, v40
	v_mul_f32_e32 v40, 0x3fb8aa3b, v40
	v_exp_f32_e32 v40, v40
	v_mul_f32_e32 v41, 0.5, v41
	v_add_f32_e32 v40, 1.0, v40
	v_div_scale_f32 v46, s[2:3], v40, v40, 2.0
	v_rcp_f32_e32 v47, v46
	s_nop 0
	v_fma_f32 v48, -v46, v47, 1.0
	v_fmac_f32_e32 v47, v48, v47
	v_div_scale_f32 v48, vcc, 2.0, v40, 2.0
	v_mul_f32_e32 v49, v48, v47
	v_fma_f32 v52, -v46, v49, v48
	v_fmac_f32_e32 v49, v52, v47
	v_fma_f32 v46, -v46, v49, v48
	v_div_fmas_f32 v46, v46, v47, v49
	v_div_fixup_f32 v40, v46, v40, 2.0
	v_sub_f32_e32 v40, 1.0, v40
	v_add_f32_e32 v40, 1.0, v40
	v_mul_f32_e32 v40, v41, v40
	v_bfe_u32 v41, v40, 16, 1
	v_add3_u32 v46, v40, v41, s31
	v_lshl_add_u64 v[40:41], s[28:29], 0, v[44:45]
	global_store_short_d16_hi v[40:41], v46, off
	v_or_b32_e32 v40, 34, v82
	v_mov_b32_e32 v41, v83
	v_lshlrev_b64 v[40:41], 9, v[40:41]
	v_lshl_add_u64 v[40:41], v[40:41], 0, v[50:51]
	v_lshlrev_b64 v[40:41], 1, v[40:41]
	v_lshl_add_u64 v[44:45], s[8:9], 0, v[40:41]
	v_lshl_add_u64 v[40:41], s[28:29], 0, v[40:41]
	s_waitcnt vmcnt(3)
; __device__ __forceinline__ float bf2f(bf16_t v) { return __uint_as_float(((unsigned)v) << 16); }
; __device__ __forceinline__ bf16_t f2bf(float f) { unsigned u = __float_as_uint(f); u += 0x7FFFu + ((u >> 16) & 1u); return (bf16_t)(u >> 16); }
; __device__ __forceinline__ void s5_bu16(const S5Frag& f, const bf16x8 uf, float* buL, int lane) {
;     const int jj = lane & 15, quad = lane >> 4;
; #pragma unroll
;     for (int nt = 0; nt < 4; ++nt) {
;         const f32x4 z = (f32x4){0.f, 0.f, 0.f, 0.f};
;         const f32x4 dre = __builtin_amdgcn_mfma_f32_16x16x32_bf16(uf, f.bfr[nt], z, 0, 0, 0);
;         const f32x4 dim = __builtin_amdgcn_mfma_f32_16x16x32_bf16(uf, f.bfr[nt + 4], z, 0, 0, 0);
; #pragma unroll
;         for (int r = 0; r < 4; ++r) *(f32x2*)(buL + ((4 * quad + r) * 64 + 16 * nt + jj) * 2) = (f32x2){dre[r], dim[r]};
;     }
; __device__ __forceinline__ void s5_pass2_item(PP p, unsigned char* shm, int item, int l) {
;     ...
;         for (int r = 0; r < 4; ++r) { const int tl = sc * 16 + quad * 4 + r;
;             const float v = y[r] + dsk * bf2f(proj[PJ_UA + (row0 + tl) * 512 + g * 16 + cc]);
;             const float z = 0.7978845608028654f * (v + 0.044715f * v * v * v);
;             const float th = 1.0f - 2.0f / (__expf(2.0f * z) + 1.0f);
;             Gout[(row0 + tl) * 512 + g * 16 + cc] = f2bf(0.5f * v * (1.0f + th)); }
	v_lshlrev_b32_e32 v44, 16, v210
	v_fma_f32 v42, v54, v44, v42
	v_mul_f32_e32 v44, 0x3d372713, v42
	v_mul_f32_e32 v44, v42, v44
	v_fma_f32 v44, v42, v44, v42
	v_mul_f32_e32 v44, 0x3f4c422a, v44
	v_add_f32_e32 v44, v44, v44
	v_mul_f32_e32 v44, 0x3fb8aa3b, v44
	v_exp_f32_e32 v44, v44
	v_mul_f32_e32 v42, 0.5, v42
	v_add_f32_e32 v44, 1.0, v44
	v_div_scale_f32 v45, s[2:3], v44, v44, 2.0
	v_rcp_f32_e32 v46, v45
	s_nop 0
	v_fma_f32 v47, -v45, v46, 1.0
	v_fmac_f32_e32 v46, v47, v46
	v_div_scale_f32 v47, vcc, 2.0, v44, 2.0
	v_mul_f32_e32 v48, v47, v46
	v_fma_f32 v49, -v45, v48, v47
	v_fmac_f32_e32 v48, v49, v46
	v_fma_f32 v45, -v45, v48, v47
	v_div_fmas_f32 v45, v45, v46, v48
	v_div_fixup_f32 v44, v45, v44, 2.0
	v_sub_f32_e32 v44, 1.0, v44
	v_add_f32_e32 v44, 1.0, v44
	v_mul_f32_e32 v42, v42, v44
	v_bfe_u32 v44, v42, 16, 1
	v_add3_u32 v42, v42, v44, s31
	global_store_short_d16_hi v[40:41], v42, off
	v_or_b32_e32 v40, 35, v82
	v_mov_b32_e32 v41, v83
	v_lshlrev_b64 v[40:41], 9, v[40:41]
	v_lshl_add_u64 v[40:41], v[40:41], 0, v[50:51]
	v_lshlrev_b64 v[40:41], 1, v[40:41]
	v_lshl_add_u64 v[44:45], s[8:9], 0, v[40:41]
	v_lshl_add_u64 v[40:41], s[28:29], 0, v[40:41]
	s_waitcnt vmcnt(3)
	v_lshlrev_b32_e32 v42, 16, v211
	v_fmac_f32_e32 v43, v54, v42
	v_mul_f32_e32 v42, 0x3d372713, v43
	v_mul_f32_e32 v42, v43, v42
	v_fma_f32 v42, v43, v42, v43
	v_mul_f32_e32 v42, 0x3f4c422a, v42
	v_add_f32_e32 v42, v42, v42
	v_mul_f32_e32 v42, 0x3fb8aa3b, v42
	v_exp_f32_e32 v42, v42
	v_mul_f32_e32 v43, 0.5, v43
	v_add_f32_e32 v42, 1.0, v42
	v_div_scale_f32 v44, s[2:3], v42, v42, 2.0
	v_rcp_f32_e32 v45, v44
	s_nop 0
	v_fma_f32 v46, -v44, v45, 1.0
	v_fmac_f32_e32 v45, v46, v45
	v_div_scale_f32 v46, vcc, 2.0, v42, 2.0
	v_mul_f32_e32 v47, v46, v45
	v_fma_f32 v48, -v44, v47, v46
	v_fmac_f32_e32 v47, v48, v45
	v_fma_f32 v44, -v44, v47, v46
	v_div_fmas_f32 v44, v44, v45, v47
	v_div_fixup_f32 v42, v44, v42, 2.0
	v_sub_f32_e32 v42, 1.0, v42
	v_add_f32_e32 v42, 1.0, v42
	v_mul_f32_e32 v42, v43, v42
	v_bfe_u32 v43, v42, 16, 1
	v_add3_u32 v42, v42, v43, s31
	global_store_short_d16_hi v[40:41], v42, off
	v_mfma_f32_16x16x32_bf16 v[40:43], v[2:5], v[26:29], 0
	s_barrier
	v_mfma_f32_16x16x32_bf16 v[26:29], v[2:5], v[34:37], 0
	v_mfma_f32_16x16x32_bf16 v[2:5], v[2:5], v[6:9], 0
	s_nop 4
	v_mov_b32_e32 v34, v40
	s_nop 0
	v_mov_b32_e32 v35, v26
	v_mov_b32_e32 v26, v41
	v_mov_b32_e32 v36, v42
	v_mov_b32_e32 v37, v28
	v_mov_b32_e32 v40, v22
	v_mov_b32_e32 v41, v30
	v_mov_b32_e32 v30, v23
	v_mov_b32_e32 v22, v24
	v_mov_b32_e32 v23, v32
	ds_write2_b64 v108, v[36:37], v[22:23] offset0:128 offset1:144
	v_mov_b32_e32 v23, v14
	v_mov_b32_e32 v14, v19
	v_mov_b32_e32 v6, v10
	v_mov_b32_e32 v7, v2
	v_mov_b32_e32 v2, v11
	v_mov_b32_e32 v28, v43
	v_mov_b32_e32 v32, v25
	v_mov_b32_e32 v22, v18
	ds_write2_b64 v108, v[30:31], v[14:15] offset0:80 offset1:96
	v_mov_b32_e32 v14, v20
	v_mov_b32_e32 v15, v16
	v_mov_b32_e32 v16, v21
	ds_write2st64_b64 v99, v[6:7], v[2:3] offset0:8 offset1:9
	v_mov_b32_e32 v2, v12
	v_mov_b32_e32 v3, v4
	v_mov_b32_e32 v4, v13
	ds_write2_b64 v108, v[34:35], v[40:41] offset1:16
	ds_write2_b64 v108, v[22:23], v[26:27] offset0:32 offset1:64
	ds_write2_b64 v108, v[14:15], v[28:29] offset0:160 offset1:192
	ds_write2_b64 v108, v[32:33], v[16:17] offset0:208 offset1:224
	ds_write2st64_b64 v99, v[2:3], v[4:5] offset0:10 offset1:11
	s_waitcnt lgkmcnt(0)
	s_barrier
	ds_read_b64 v[2:3], v90 offset:4096
	v_xor_b32_e32 v4, 0x80000000, v39
	v_mov_b32_e32 v5, v38
	v_pk_mul_f32 v[4:5], v[0:1], v[4:5] op_sel_hi:[0,1]
	v_pk_fma_f32 v[4:5], v[84:85], v[38:39], v[4:5] op_sel_hi:[0,1,1]
	s_waitcnt lgkmcnt(0)
	v_pk_add_f32 v[2:3], v[4:5], v[2:3]
	ds_write2st64_b32 v98, v2, v3 offset1:1
	ds_read_b64 v[4:5], v90 offset:4608
	v_xor_b32_e32 v6, 0x80000000, v3
	v_mov_b32_e32 v7, v2
	v_pk_mul_f32 v[6:7], v[0:1], v[6:7] op_sel_hi:[0,1]
	v_pk_fma_f32 v[2:3], v[84:85], v[2:3], v[6:7] op_sel_hi:[0,1,1]
	s_waitcnt lgkmcnt(0)
	v_pk_add_f32 v[2:3], v[4:5], v[2:3]
	ds_write2_b32 v98, v2, v3 offset0:132 offset1:196
	ds_read_b64 v[4:5], v90 offset:5120
	v_xor_b32_e32 v6, 0x80000000, v3
	v_mov_b32_e32 v7, v2
	v_pk_mul_f32 v[6:7], v[0:1], v[6:7] op_sel_hi:[0,1]
	v_pk_fma_f32 v[2:3], v[84:85], v[2:3], v[6:7] op_sel_hi:[0,1,1]
	s_waitcnt lgkmcnt(0)
	v_pk_add_f32 v[2:3], v[4:5], v[2:3]
	ds_write2st64_b32 v78, v2, v3 offset0:4 offset1:5
	ds_read_b64 v[4:5], v90 offset:5632
	v_xor_b32_e32 v6, 0x80000000, v3
	v_mov_b32_e32 v7, v2
	v_pk_mul_f32 v[6:7], v[0:1], v[6:7] op_sel_hi:[0,1]
	v_pk_fma_f32 v[2:3], v[84:85], v[2:3], v[6:7] op_sel_hi:[0,1,1]
	s_waitcnt lgkmcnt(0)
	v_pk_add_f32 v[2:3], v[4:5], v[2:3]
	ds_write2st64_b32 v79, v2, v3 offset0:6 offset1:7
	ds_read_b64 v[4:5], v90 offset:6144
	v_xor_b32_e32 v6, 0x80000000, v3
	v_mov_b32_e32 v7, v2
	v_pk_mul_f32 v[6:7], v[0:1], v[6:7] op_sel_hi:[0,1]
	v_pk_fma_f32 v[2:3], v[84:85], v[2:3], v[6:7] op_sel_hi:[0,1,1]
	s_waitcnt lgkmcnt(0)
	v_pk_add_f32 v[2:3], v[4:5], v[2:3]
	ds_write2st64_b32 v80, v2, v3 offset0:8 offset1:9
	ds_read_b64 v[4:5], v90 offset:6656
	v_xor_b32_e32 v6, 0x80000000, v3
	v_mov_b32_e32 v7, v2
	v_pk_mul_f32 v[6:7], v[0:1], v[6:7] op_sel_hi:[0,1]
	v_pk_fma_f32 v[2:3], v[84:85], v[2:3], v[6:7] op_sel_hi:[0,1,1]
	s_waitcnt lgkmcnt(0)
	v_pk_add_f32 v[2:3], v[4:5], v[2:3]
	ds_write2st64_b32 v81, v2, v3 offset0:10 offset1:11
	ds_read_b64 v[4:5], v90 offset:7168
	v_xor_b32_e32 v6, 0x80000000, v3
	v_mov_b32_e32 v7, v2
	v_pk_mul_f32 v[6:7], v[0:1], v[6:7] op_sel_hi:[0,1]
	v_pk_fma_f32 v[2:3], v[84:85], v[2:3], v[6:7] op_sel_hi:[0,1,1]
	s_waitcnt lgkmcnt(0)
; __device__ __forceinline__ void s5_pass2_item(PP p, unsigned char* shm, int item, int l) {
;     ...
; #pragma unroll
;         for (int t = 0; t < 16; ++t) { s5_rec(q, *(const f32x2*)(buL + (t * 64 + lane) * 2), x); xs[t * 132 + lane] = x.x; xs[t * 132 + 64 + lane] = x.y; }
;         __syncthreads();
	v_pk_add_f32 v[2:3], v[4:5], v[2:3]
	ds_write2st64_b32 v86, v2, v3 offset0:12 offset1:13
	ds_read_b64 v[4:5], v90 offset:7680
	v_xor_b32_e32 v6, 0x80000000, v3
	v_mov_b32_e32 v7, v2
	v_pk_mul_f32 v[6:7], v[0:1], v[6:7] op_sel_hi:[0,1]
	v_pk_fma_f32 v[2:3], v[84:85], v[2:3], v[6:7] op_sel_hi:[0,1,1]
	s_waitcnt lgkmcnt(0)
	v_pk_add_f32 v[2:3], v[4:5], v[2:3]
	ds_write2st64_b32 v87, v2, v3 offset0:14 offset1:15
	ds_read_b64 v[4:5], v90 offset:8192
	v_xor_b32_e32 v6, 0x80000000, v3
	v_mov_b32_e32 v7, v2
	v_pk_mul_f32 v[6:7], v[0:1], v[6:7] op_sel_hi:[0,1]
	v_pk_fma_f32 v[2:3], v[84:85], v[2:3], v[6:7] op_sel_hi:[0,1,1]
	s_waitcnt lgkmcnt(0)
	v_pk_add_f32 v[2:3], v[4:5], v[2:3]
	ds_write2st64_b32 v100, v2, v3 offset0:16 offset1:17
	ds_read_b64 v[4:5], v90 offset:8704
	v_xor_b32_e32 v6, 0x80000000, v3
	v_mov_b32_e32 v7, v2
	v_pk_mul_f32 v[6:7], v[0:1], v[6:7] op_sel_hi:[0,1]
	v_pk_fma_f32 v[2:3], v[84:85], v[2:3], v[6:7] op_sel_hi:[0,1,1]
	s_waitcnt lgkmcnt(0)
	v_pk_add_f32 v[2:3], v[4:5], v[2:3]
	ds_write2st64_b32 v101, v2, v3 offset0:18 offset1:19
	ds_read_b64 v[4:5], v90 offset:9216
	v_xor_b32_e32 v6, 0x80000000, v3
	v_mov_b32_e32 v7, v2
	v_pk_mul_f32 v[6:7], v[0:1], v[6:7] op_sel_hi:[0,1]
	v_pk_fma_f32 v[2:3], v[84:85], v[2:3], v[6:7] op_sel_hi:[0,1,1]
	s_waitcnt lgkmcnt(0)
	v_pk_add_f32 v[2:3], v[4:5], v[2:3]
	ds_write2st64_b32 v102, v2, v3 offset0:20 offset1:21
	ds_read_b64 v[4:5], v90 offset:9728
	v_xor_b32_e32 v6, 0x80000000, v3
	v_mov_b32_e32 v7, v2
	v_pk_mul_f32 v[6:7], v[0:1], v[6:7] op_sel_hi:[0,1]
	v_pk_fma_f32 v[2:3], v[84:85], v[2:3], v[6:7] op_sel_hi:[0,1,1]
	s_waitcnt lgkmcnt(0)
	v_pk_add_f32 v[2:3], v[4:5], v[2:3]
	ds_write2st64_b32 v103, v2, v3 offset0:22 offset1:23
	ds_read_b64 v[4:5], v90 offset:10240
	v_xor_b32_e32 v6, 0x80000000, v3
	v_mov_b32_e32 v7, v2
	v_pk_mul_f32 v[6:7], v[0:1], v[6:7] op_sel_hi:[0,1]
	v_pk_fma_f32 v[2:3], v[84:85], v[2:3], v[6:7] op_sel_hi:[0,1,1]
	s_waitcnt lgkmcnt(0)
	v_pk_add_f32 v[2:3], v[4:5], v[2:3]
	ds_write2st64_b32 v104, v2, v3 offset0:24 offset1:25
	ds_read_b64 v[4:5], v90 offset:10752
	v_xor_b32_e32 v6, 0x80000000, v3
	v_mov_b32_e32 v7, v2
	v_pk_mul_f32 v[6:7], v[0:1], v[6:7] op_sel_hi:[0,1]
	v_pk_fma_f32 v[2:3], v[84:85], v[2:3], v[6:7] op_sel_hi:[0,1,1]
	s_waitcnt lgkmcnt(0)
	v_pk_add_f32 v[2:3], v[4:5], v[2:3]
	ds_write2st64_b32 v105, v2, v3 offset0:26 offset1:27
	ds_read_b64 v[4:5], v90 offset:11264
	v_xor_b32_e32 v6, 0x80000000, v3
	v_mov_b32_e32 v7, v2
	v_pk_mul_f32 v[6:7], v[0:1], v[6:7] op_sel_hi:[0,1]
	v_pk_fma_f32 v[2:3], v[84:85], v[2:3], v[6:7] op_sel_hi:[0,1,1]
	s_waitcnt lgkmcnt(0)
	v_pk_add_f32 v[2:3], v[4:5], v[2:3]
	ds_write2st64_b32 v106, v2, v3 offset0:28 offset1:29
	ds_read_b64 v[4:5], v90 offset:11776
	v_xor_b32_e32 v6, 0x80000000, v3
	v_mov_b32_e32 v7, v2
	v_pk_mul_f32 v[6:7], v[0:1], v[6:7] op_sel_hi:[0,1]
	v_pk_fma_f32 v[2:3], v[84:85], v[2:3], v[6:7] op_sel_hi:[0,1,1]
	s_waitcnt lgkmcnt(0)
	v_pk_add_f32 v[2:3], v[4:5], v[2:3]
	ds_write2st64_b32 v107, v2, v3 offset0:30 offset1:31
	s_waitcnt lgkmcnt(0)
	s_barrier
; __device__ __forceinline__ float bf2f(bf16_t v) { return __uint_as_float(((unsigned)v) << 16); }
; __device__ __forceinline__ bf16_t f2bf(float f) { unsigned u = __float_as_uint(f); u += 0x7FFFu + ((u >> 16) & 1u); return (bf16_t)(u >> 16); }
; __device__ __forceinline__ void s5_pass2_item(PP p, unsigned char* shm, int item, int l) {
;     ...
;         f32x4 y0 = (f32x4){0.f, 0.f, 0.f, 0.f}, y1 = y0;
;         const f32x4* xrow = (const f32x4*)(xs + cc * 132 + quad * 32);
; #pragma unroll
;         for (int i = 0; i < 8; ++i) { const f32x4 xv = xrow[i];
;             y0 = __builtin_amdgcn_mfma_f32_16x16x4f32(xv[0], cmr[4 * i + 0], y0, 0, 0, 0);
;             y1 = __builtin_amdgcn_mfma_f32_16x16x4f32(xv[1], cmr[4 * i + 1], y1, 0, 0, 0);
;             y0 = __builtin_amdgcn_mfma_f32_16x16x4f32(xv[2], cmr[4 * i + 2], y0, 0, 0, 0);
;             y1 = __builtin_amdgcn_mfma_f32_16x16x4f32(xv[3], cmr[4 * i + 3], y1, 0, 0, 0); }
;         const f32x4 y = y0 + y1;
; #pragma unroll
;         for (int r = 0; r < 4; ++r) { const int tl = sc * 16 + quad * 4 + r;
;             const float v = y[r] + dsk * bf2f(proj[PJ_UA + (row0 + tl) * 512 + g * 16 + cc]);
;             const float z = 0.7978845608028654f * (v + 0.044715f * v * v * v);
;             const float th = 1.0f - 2.0f / (__expf(2.0f * z) + 1.0f);
;             Gout[(row0 + tl) * 512 + g * 16 + cc] = f2bf(0.5f * v * (1.0f + th)); }
	v_or_b32_e32 v216, 48, v82
	v_mov_b32_e32 v217, v83
	v_lshlrev_b64 v[216:217], 9, v[216:217]
	v_lshl_add_u64 v[216:217], v[216:217], 0, v[50:51]
	v_lshlrev_b64 v[216:217], 1, v[216:217]
	v_lshl_add_u64 v[216:217], s[8:9], 0, v[216:217]
	global_load_ushort v212, v[216:217], off
	global_load_ushort v213, v[216:217], off offset:1024
	global_load_ushort v214, v[216:217], off offset:2048
	global_load_ushort v215, v[216:217], off offset:3072
	ds_read_b128 v[2:5], v89
	ds_read_b128 v[6:9], v89 offset:16
	ds_read_b128 v[10:13], v89 offset:32
	ds_read_b128 v[14:17], v89 offset:48
	s_waitcnt lgkmcnt(3)
	v_mfma_f32_16x16x4_f32 v[18:21], v2, v97, 0
	v_mfma_f32_16x16x4_f32 v[22:25], v3, v96, 0
	v_mfma_f32_16x16x4_f32 v[18:21], v4, v95, v[18:21]
	v_mfma_f32_16x16x4_f32 v[2:5], v5, v94, v[22:25]
	s_waitcnt lgkmcnt(2)
	v_mfma_f32_16x16x4_f32 v[18:21], v6, v93, v[18:21]
	v_mfma_f32_16x16x4_f32 v[2:5], v7, v92, v[2:5]
	v_mfma_f32_16x16x4_f32 v[18:21], v8, v91, v[18:21]
	v_mfma_f32_16x16x4_f32 v[2:5], v9, v88, v[2:5]
	s_waitcnt lgkmcnt(1)
	v_mfma_f32_16x16x4_f32 v[6:9], v10, v85, v[18:21]
	v_mfma_f32_16x16x4_f32 v[2:5], v11, v55, v[2:5]
	v_mfma_f32_16x16x4_f32 v[6:9], v12, v56, v[6:9]
	v_mfma_f32_16x16x4_f32 v[2:5], v13, v57, v[2:5]
	ds_read_b128 v[10:13], v89 offset:64
	s_waitcnt lgkmcnt(1)
	v_mfma_f32_16x16x4_f32 v[6:9], v14, v58, v[6:9]
	v_mfma_f32_16x16x4_f32 v[2:5], v15, v59, v[2:5]
	v_mfma_f32_16x16x4_f32 v[6:9], v16, v60, v[6:9]
	v_mfma_f32_16x16x4_f32 v[2:5], v17, v61, v[2:5]
	s_waitcnt lgkmcnt(0)
	v_mfma_f32_16x16x4_f32 v[6:9], v10, v62, v[6:9]
	v_mfma_f32_16x16x4_f32 v[2:5], v11, v63, v[2:5]
	v_mfma_f32_16x16x4_f32 v[6:9], v12, v64, v[6:9]
	v_mfma_f32_16x16x4_f32 v[2:5], v13, v65, v[2:5]
	ds_read_b128 v[10:13], v89 offset:80
	s_waitcnt lgkmcnt(0)
	v_mfma_f32_16x16x4_f32 v[6:9], v10, v66, v[6:9]
	v_mfma_f32_16x16x4_f32 v[2:5], v11, v67, v[2:5]
	v_mfma_f32_16x16x4_f32 v[6:9], v12, v68, v[6:9]
	v_mfma_f32_16x16x4_f32 v[2:5], v13, v69, v[2:5]
	ds_read_b128 v[10:13], v89 offset:96
	s_waitcnt lgkmcnt(0)
	v_mfma_f32_16x16x4_f32 v[6:9], v10, v70, v[6:9]
	v_mfma_f32_16x16x4_f32 v[2:5], v11, v71, v[2:5]
	v_mfma_f32_16x16x4_f32 v[6:9], v12, v72, v[6:9]
	v_mfma_f32_16x16x4_f32 v[2:5], v13, v73, v[2:5]
	ds_read_b128 v[10:13], v89 offset:112
	s_waitcnt lgkmcnt(0)
	v_mfma_f32_16x16x4_f32 v[6:9], v10, v74, v[6:9]
	v_mfma_f32_16x16x4_f32 v[2:5], v11, v75, v[2:5]
	v_mfma_f32_16x16x4_f32 v[6:9], v12, v76, v[6:9]
	v_mfma_f32_16x16x4_f32 v[10:13], v13, v77, v[2:5]
	s_nop 9
	v_pk_add_f32 v[4:5], v[6:7], v[10:11]
	v_or_b32_e32 v6, 48, v82
	v_mov_b32_e32 v7, v83
	v_lshlrev_b64 v[6:7], 9, v[6:7]
	v_lshl_add_u64 v[6:7], v[6:7], 0, v[50:51]
	v_lshlrev_b64 v[6:7], 1, v[6:7]
	v_pk_add_f32 v[2:3], v[8:9], v[12:13]
	v_lshl_add_u64 v[8:9], s[8:9], 0, v[6:7]
	v_lshl_add_u64 v[6:7], s[28:29], 0, v[6:7]
	s_waitcnt vmcnt(3)
	v_lshlrev_b32_e32 v0, 16, v212
	v_fma_f32 v0, v54, v0, v4
	v_mul_f32_e32 v4, 0x3d372713, v0
	v_mul_f32_e32 v4, v0, v4
	v_fma_f32 v4, v0, v4, v0
	v_mul_f32_e32 v4, 0x3f4c422a, v4
	v_add_f32_e32 v4, v4, v4
	v_mul_f32_e32 v4, 0x3fb8aa3b, v4
	v_exp_f32_e32 v4, v4
	v_mul_f32_e32 v0, 0.5, v0
	v_add_f32_e32 v4, 1.0, v4
	v_div_scale_f32 v8, s[2:3], v4, v4, 2.0
	v_rcp_f32_e32 v9, v8
	s_nop 0
	v_fma_f32 v10, -v8, v9, 1.0
	v_fmac_f32_e32 v9, v10, v9
	v_div_scale_f32 v10, vcc, 2.0, v4, 2.0
	v_mul_f32_e32 v11, v10, v9
	v_fma_f32 v12, -v8, v11, v10
	v_fmac_f32_e32 v11, v12, v9
	v_fma_f32 v8, -v8, v11, v10
	v_div_fmas_f32 v8, v8, v9, v11
	v_div_fixup_f32 v4, v8, v4, 2.0
	v_sub_f32_e32 v4, 1.0, v4
	v_add_f32_e32 v4, 1.0, v4
	v_mul_f32_e32 v0, v0, v4
	v_bfe_u32 v4, v0, 16, 1
	v_add3_u32 v0, v0, v4, s31
	global_store_short_d16_hi v[6:7], v0, off
	v_or_b32_e32 v6, 49, v82
	v_mov_b32_e32 v7, v83
	v_lshlrev_b64 v[6:7], 9, v[6:7]
	v_lshl_add_u64 v[6:7], v[6:7], 0, v[50:51]
	v_lshlrev_b64 v[6:7], 1, v[6:7]
	v_lshl_add_u64 v[8:9], s[8:9], 0, v[6:7]
	s_waitcnt vmcnt(3)
	v_lshlrev_b32_e32 v0, 16, v213
	v_fmac_f32_e32 v5, v54, v0
	v_mul_f32_e32 v0, 0x3d372713, v5
	v_mul_f32_e32 v0, v5, v0
	v_fma_f32 v0, v5, v0, v5
	v_mul_f32_e32 v0, 0x3f4c422a, v0
	v_add_f32_e32 v0, v0, v0
	v_mul_f32_e32 v0, 0x3fb8aa3b, v0
	v_exp_f32_e32 v0, v0
	s_nop 0
	v_add_f32_e32 v0, 1.0, v0
	v_div_scale_f32 v4, s[2:3], v0, v0, 2.0
	v_rcp_f32_e32 v8, v4
	s_nop 0
	v_fma_f32 v9, -v4, v8, 1.0
	v_fmac_f32_e32 v8, v9, v8
	v_div_scale_f32 v9, vcc, 2.0, v0, 2.0
	v_mul_f32_e32 v10, v9, v8
	v_fma_f32 v11, -v4, v10, v9
	v_fmac_f32_e32 v10, v11, v8
	v_fma_f32 v4, -v4, v10, v9
	v_div_fmas_f32 v4, v4, v8, v10
	v_div_fixup_f32 v0, v4, v0, 2.0
	v_sub_f32_e32 v0, 1.0, v0
	v_mul_f32_e32 v4, 0.5, v5
	v_add_f32_e32 v0, 1.0, v0
	v_mul_f32_e32 v0, v4, v0
	v_bfe_u32 v4, v0, 16, 1
	v_add3_u32 v0, v0, v4, s31
	v_lshl_add_u64 v[4:5], s[28:29], 0, v[6:7]
	global_store_short_d16_hi v[4:5], v0, off
	v_or_b32_e32 v4, 50, v82
	v_mov_b32_e32 v5, v83
	v_lshlrev_b64 v[4:5], 9, v[4:5]
	v_lshl_add_u64 v[4:5], v[4:5], 0, v[50:51]
	v_lshlrev_b64 v[4:5], 1, v[4:5]
	v_lshl_add_u64 v[6:7], s[8:9], 0, v[4:5]
	v_lshl_add_u64 v[4:5], s[28:29], 0, v[4:5]
	v_or_b32_e32 v82, 51, v82
	s_waitcnt vmcnt(3)
	v_lshlrev_b32_e32 v0, 16, v214
	v_fma_f32 v0, v54, v0, v2
	v_mul_f32_e32 v2, 0x3d372713, v0
	v_mul_f32_e32 v2, v0, v2
	v_fma_f32 v2, v0, v2, v0
	v_mul_f32_e32 v2, 0x3f4c422a, v2
	v_add_f32_e32 v2, v2, v2
	v_mul_f32_e32 v2, 0x3fb8aa3b, v2
	v_exp_f32_e32 v2, v2
	v_mul_f32_e32 v0, 0.5, v0
	v_add_f32_e32 v2, 1.0, v2
	v_div_scale_f32 v6, s[2:3], v2, v2, 2.0
	v_rcp_f32_e32 v7, v6
	s_nop 0
	v_fma_f32 v8, -v6, v7, 1.0
	v_fmac_f32_e32 v7, v8, v7
	v_div_scale_f32 v8, vcc, 2.0, v2, 2.0
	v_mul_f32_e32 v9, v8, v7
	v_fma_f32 v10, -v6, v9, v8
	v_fmac_f32_e32 v9, v10, v7
	v_fma_f32 v6, -v6, v9, v8
	v_div_fmas_f32 v6, v6, v7, v9
	v_div_fixup_f32 v2, v6, v2, 2.0
	v_sub_f32_e32 v2, 1.0, v2
	v_add_f32_e32 v2, 1.0, v2
	v_mul_f32_e32 v0, v0, v2
	v_bfe_u32 v2, v0, 16, 1
	v_add3_u32 v0, v0, v2, s31
	global_store_short_d16_hi v[4:5], v0, off
	v_lshlrev_b64 v[4:5], 9, v[82:83]
	v_lshl_add_u64 v[4:5], v[4:5], 0, v[50:51]
	v_lshlrev_b64 v[4:5], 1, v[4:5]
	v_lshl_add_u64 v[6:7], s[8:9], 0, v[4:5]
	s_waitcnt vmcnt(3)
	v_lshlrev_b32_e32 v0, 16, v215
	v_fmac_f32_e32 v3, v54, v0
	v_mul_f32_e32 v0, 0x3d372713, v3
	v_mul_f32_e32 v0, v3, v0
	v_fma_f32 v0, v3, v0, v3
	v_mul_f32_e32 v0, 0x3f4c422a, v0
	v_add_f32_e32 v0, v0, v0
	v_mul_f32_e32 v0, 0x3fb8aa3b, v0
	v_exp_f32_e32 v0, v0
	s_nop 0
	v_add_f32_e32 v0, 1.0, v0
	v_div_scale_f32 v2, s[2:3], v0, v0, 2.0
	v_rcp_f32_e32 v6, v2
	s_nop 0
	v_fma_f32 v7, -v2, v6, 1.0
	v_fmac_f32_e32 v6, v7, v6
	v_div_scale_f32 v7, vcc, 2.0, v0, 2.0
	v_mul_f32_e32 v8, v7, v6
	v_fma_f32 v9, -v2, v8, v7
	v_fmac_f32_e32 v8, v9, v6
	v_fma_f32 v2, -v2, v8, v7
	v_div_fmas_f32 v2, v2, v6, v8
	v_div_fixup_f32 v0, v2, v0, 2.0
	v_sub_f32_e32 v0, 1.0, v0
	v_mul_f32_e32 v2, 0.5, v3
	v_add_f32_e32 v0, 1.0, v0
	v_mul_f32_e32 v0, v2, v0
	v_bfe_u32 v2, v0, 16, 1
	v_add3_u32 v0, v0, v2, s31
	v_lshl_add_u64 v[2:3], s[28:29], 0, v[4:5]
	global_store_short_d16_hi v[2:3], v0, off
	s_barrier
	s_cbranch_scc1 .LBB0_718
